# attention: 3-slot LDS ring with one barrier per key pair (staging published at mid-pair)
# baseline (speedup 1.0000x reference)
; __device__ __forceinline__ void gdn_scan_item(const Ctx& a, int l, int b, int h, int half, LAS unsigned char* lds, int variant) {
;     ...
;         for (int n = 0; n < 128; ++n) {
;             const int bufi = n & 1;
;             if (variant == 2) { GS_BAR(); continue; }
;             LAS unsigned char* Bf = lds + bufi * GS_BUF;
;             const LAS bf16_t* Wb = (const LAS bf16_t*)(Bf + GS_W); const LAS bf16_t* Qb = (const LAS bf16_t*)(Bf + GS_Q);
;             const LAS bf16_t* Kt = (const LAS bf16_t*)(Bf + GS_K); const LAS bf16_t* QKb = (const LAS bf16_t*)(Bf + GS_QK);
;             f32x16 vn[2], o[2];
;             const float gl = gl_next;
; #pragma unroll
;             for (int tb = 0; tb < 2; ++tb)
; #pragma unroll
;                 for (int r = 0; r < 16; ++r) { vn[tb][r] = 0.f; o[tb][r] = 0.f; }
;             bf16x8 aop[16];
; #pragma unroll
;             for (int kb = 0; kb < 4; ++kb) {
; #pragma unroll
;                 for (int c = 0; c < 2; ++c)
; #pragma unroll
;                     for (int tb = 0; tb < 2; ++tb) {
;                         aop[c * 2 + tb] = lds_a2(Wb + (tb * 32 + l32) * 132 + kb * 32 + c * 16 + hb * 4);
;                         aop[4 + c * 2 + tb] = lds_a2(Qb + (tb * 32 + l32) * 132 + kb * 32 + c * 16 + hb * 4);
;                     }
;                 __builtin_amdgcn_sched_barrier(0);
; #pragma unroll
;                 for (int c = 0; c < 2; ++c) {
;                     bf16x8 sb = pack8(S[kb], c);
; #pragma unroll
;                     for (int tb = 0; tb < 2; ++tb) {
;                         vn[tb] = __builtin_amdgcn_mfma_f32_32x32x16_bf16(aop[c * 2 + tb], sb, vn[tb], 0, 0, 0);
;                         o[tb] = __builtin_amdgcn_mfma_f32_32x32x16_bf16(aop[4 + c * 2 + tb], sb, o[tb], 0, 0, 0);
;                     }
;                 }
;                 __builtin_amdgcn_sched_barrier(0);
;             }
;             bf16x8 vb[2][2];
; #pragma unroll
;             for (int tb = 0; tb < 2; ++tb) {
; #pragma unroll
;                 for (int r = 0; r < 16; ++r) { unsigned uw = U[tb][r >> 3][(r >> 1) & 3]; vn[tb][r] = ((r & 1) ? hi_bf(uw) : lo_bf(uw)) - vn[tb][r]; }
;                 vb[tb][0] = pack8(vn[tb], 0); vb[tb][1] = pack8(vn[tb], 1);
;             }
;             __builtin_amdgcn_sched_barrier(0);
;             { const int n1_ = (n + 1 < 128) ? n + 1 : 127; GS_LOADU(n1_); }
;             bf16x8 qop[8];
.Lsc0_loop:
	s_waitcnt vmcnt(0)
	v_mul_f32 v187, 0x3fb8aa3b, v181
	v_exp_f32 v187, v187
	s_nop 7
	s_nop 0
	v_lshlrev_b32 v80, 16, v162
	v_and_b32 v81, 0xffff0000, v162
	v_lshlrev_b32 v82, 16, v163
	v_and_b32 v83, 0xffff0000, v163
	v_lshlrev_b32 v84, 16, v164
	v_and_b32 v85, 0xffff0000, v164
	v_lshlrev_b32 v86, 16, v165
	v_and_b32 v87, 0xffff0000, v165
	v_lshlrev_b32 v88, 16, v166
	v_and_b32 v89, 0xffff0000, v166
	v_lshlrev_b32 v90, 16, v167
	v_and_b32 v91, 0xffff0000, v167
	v_lshlrev_b32 v92, 16, v168
	v_and_b32 v93, 0xffff0000, v168
	v_lshlrev_b32 v94, 16, v169
	v_and_b32 v95, 0xffff0000, v169
	v_lshlrev_b32 v96, 16, v170
	v_and_b32 v97, 0xffff0000, v170
	v_lshlrev_b32 v98, 16, v171
	v_and_b32 v99, 0xffff0000, v171
	v_lshlrev_b32 v100, 16, v172
	v_and_b32 v101, 0xffff0000, v172
	v_lshlrev_b32 v102, 16, v173
	v_and_b32 v103, 0xffff0000, v173
	v_lshlrev_b32 v104, 16, v174
	v_and_b32 v105, 0xffff0000, v174
	v_lshlrev_b32 v106, 16, v175
	v_and_b32 v107, 0xffff0000, v175
	v_lshlrev_b32 v108, 16, v176
	v_and_b32 v109, 0xffff0000, v176
	v_lshlrev_b32 v110, 16, v177
	v_and_b32 v111, 0xffff0000, v177
	global_load_dwordx4 v[162:165], v186, s[36:37] offset:0
	global_load_dwordx4 v[166:169], v186, s[36:37] offset:16
	global_load_dwordx4 v[170:173], v186, s[36:37] offset:2048
	global_load_dwordx4 v[174:177], v186, s[36:37] offset:2064
	global_load_dword v181, v3, s[38:39]
	s_add_u32 s36, s36, 0x4000
	s_addc_u32 s37, s37, 0
	s_add_u32 s38, s38, 4
	s_addc_u32 s39, s39, 0
	ds_read_b64 v[200:201], v184 offset:0
	ds_read_b64 v[202:203], v184 offset:16
	ds_read_b64 v[204:205], v184 offset:8448
	ds_read_b64 v[206:207], v184 offset:8464
	ds_read_b64 v[208:209], v184 offset:32
	ds_read_b64 v[210:211], v184 offset:48
	ds_read_b64 v[212:213], v184 offset:8480
	ds_read_b64 v[214:215], v184 offset:8496
	ds_read_b64 v[216:217], v184 offset:64
	ds_read_b64 v[218:219], v184 offset:80
	s_waitcnt lgkmcnt(8)
	v_mfma_f32_32x32x16_bf16 v[80:95], v[200:203], v[112:115], v[80:95]
	ds_read_b64 v[220:221], v184 offset:8512
	ds_read_b64 v[222:223], v184 offset:8528
	v_mul_f32 v16, v16, v187
	v_mul_f32 v17, v17, v187
	v_mul_f32 v18, v18, v187
	v_mul_f32 v19, v19, v187
	s_waitcnt lgkmcnt(8)
	v_mfma_f32_32x32x16_bf16 v[96:111], v[204:207], v[112:115], v[96:111]
	ds_read_b64 v[200:201], v184 offset:96
	ds_read_b64 v[202:203], v184 offset:112
	v_mul_f32 v20, v20, v187
	v_mul_f32 v21, v21, v187
	v_mul_f32 v22, v22, v187
	v_mul_f32 v23, v23, v187
	s_waitcnt lgkmcnt(8)
	v_mfma_f32_32x32x16_bf16 v[80:95], v[208:211], v[116:119], v[80:95]
	ds_read_b64 v[204:205], v184 offset:8544
	ds_read_b64 v[206:207], v184 offset:8560
	v_mul_f32 v24, v24, v187
	v_mul_f32 v25, v25, v187
	v_mul_f32 v26, v26, v187
	v_mul_f32 v27, v27, v187
	s_waitcnt lgkmcnt(8)
	v_mfma_f32_32x32x16_bf16 v[96:111], v[212:215], v[116:119], v[96:111]
	ds_read_b64 v[208:209], v184 offset:128
	ds_read_b64 v[210:211], v184 offset:144
	v_mul_f32 v28, v28, v187
	v_mul_f32 v29, v29, v187
	v_mul_f32 v30, v30, v187
	v_mul_f32 v31, v31, v187
	s_waitcnt lgkmcnt(8)
	v_mfma_f32_32x32x16_bf16 v[80:95], v[216:219], v[120:123], v[80:95]
	ds_read_b64 v[212:213], v184 offset:8576
	ds_read_b64 v[214:215], v184 offset:8592
	v_mul_f32 v32, v32, v187
	v_mul_f32 v33, v33, v187
	v_mul_f32 v34, v34, v187
	v_mul_f32 v35, v35, v187
	s_waitcnt lgkmcnt(8)
	v_mfma_f32_32x32x16_bf16 v[96:111], v[220:223], v[120:123], v[96:111]
	ds_read_b64 v[216:217], v184 offset:160
	ds_read_b64 v[218:219], v184 offset:176
	v_mul_f32 v36, v36, v187
	v_mul_f32 v37, v37, v187
	v_mul_f32 v38, v38, v187
	v_mul_f32 v39, v39, v187
	s_waitcnt lgkmcnt(8)
	v_mfma_f32_32x32x16_bf16 v[80:95], v[200:203], v[124:127], v[80:95]
	ds_read_b64 v[220:221], v184 offset:8608
	ds_read_b64 v[222:223], v184 offset:8624
	v_mul_f32 v40, v40, v187
	v_mul_f32 v41, v41, v187
	v_mul_f32 v42, v42, v187
	v_mul_f32 v43, v43, v187
	s_waitcnt lgkmcnt(8)
	v_mfma_f32_32x32x16_bf16 v[96:111], v[204:207], v[124:127], v[96:111]
	ds_read_b64 v[200:201], v184 offset:192
	ds_read_b64 v[202:203], v184 offset:208
	v_mul_f32 v44, v44, v187
	v_mul_f32 v45, v45, v187
	v_mul_f32 v46, v46, v187
	v_mul_f32 v47, v47, v187
	s_waitcnt lgkmcnt(8)
	v_mfma_f32_32x32x16_bf16 v[80:95], v[208:211], v[128:131], v[80:95]
	ds_read_b64 v[204:205], v184 offset:8640
	ds_read_b64 v[206:207], v184 offset:8656
	v_mul_f32 v48, v48, v187
	v_mul_f32 v49, v49, v187
	v_mul_f32 v50, v50, v187
	v_mul_f32 v51, v51, v187
	s_waitcnt lgkmcnt(8)
	v_mfma_f32_32x32x16_bf16 v[96:111], v[212:215], v[128:131], v[96:111]
	ds_read_b64 v[208:209], v184 offset:224
	ds_read_b64 v[210:211], v184 offset:240
	v_mul_f32 v52, v52, v187
	v_mul_f32 v53, v53, v187
	v_mul_f32 v54, v54, v187
	v_mul_f32 v55, v55, v187
	s_waitcnt lgkmcnt(8)
	v_mfma_f32_32x32x16_bf16 v[80:95], v[216:219], v[132:135], v[80:95]
	ds_read_b64 v[212:213], v184 offset:8672
	ds_read_b64 v[214:215], v184 offset:8688
	v_mul_f32 v56, v56, v187
	v_mul_f32 v57, v57, v187
	v_mul_f32 v58, v58, v187
	v_mul_f32 v59, v59, v187
	s_waitcnt lgkmcnt(8)
	v_mfma_f32_32x32x16_bf16 v[96:111], v[220:223], v[132:135], v[96:111]
	v_mul_f32 v60, v60, v187
	v_mul_f32 v61, v61, v187
	v_mul_f32 v62, v62, v187
	v_mul_f32 v63, v63, v187
	s_waitcnt lgkmcnt(6)
	v_mfma_f32_32x32x16_bf16 v[80:95], v[200:203], v[136:139], v[80:95]
	v_mul_f32 v64, v64, v187
	v_mul_f32 v65, v65, v187
	v_mul_f32 v66, v66, v187
	v_mul_f32 v67, v67, v187
	s_waitcnt lgkmcnt(4)
	v_mfma_f32_32x32x16_bf16 v[96:111], v[204:207], v[136:139], v[96:111]
	v_mul_f32 v68, v68, v187
	v_mul_f32 v69, v69, v187
	v_mul_f32 v70, v70, v187
	v_mul_f32 v71, v71, v187
	s_waitcnt lgkmcnt(2)
; __device__ __forceinline__ float lo_bf(unsigned u) { return __uint_as_float(u << 16); }
; __device__ __forceinline__ float hi_bf(unsigned u) { return __uint_as_float(u & 0xffff0000u); }
; #define GS_LOADU(n) do { const bf16_t* up_ = gu + ((size_t)((h * 128 + (n)) * 4 + half) * 2) * 1024 + lane * 16; \
;     _Pragma("unroll") for (int tb_ = 0; tb_ < 2; ++tb_) { U[tb_][0] = *(const u32x4*)(up_ + tb_ * 1024); U[tb_][1] = *(const u32x4*)(up_ + tb_ * 1024 + 8); } \
;     gl_next = __expf(glast[h * 128 + (n)]); } while (0)
; __device__ __forceinline__ void gdn_scan_item(const Ctx& a, int l, int b, int h, int half, LAS unsigned char* lds, int variant) {
;     ...
;                         vn[tb] = __builtin_amdgcn_mfma_f32_32x32x16_bf16(aop[c * 2 + tb], sb, vn[tb], 0, 0, 0);
;                         o[tb] = __builtin_amdgcn_mfma_f32_32x32x16_bf16(aop[4 + c * 2 + tb], sb, o[tb], 0, 0, 0);
;                     }
;                 }
;                 __builtin_amdgcn_sched_barrier(0);
;             }
;             bf16x8 vb[2][2];
; #pragma unroll
;             for (int tb = 0; tb < 2; ++tb) {
; #pragma unroll
;                 for (int r = 0; r < 16; ++r) { unsigned uw = U[tb][r >> 3][(r >> 1) & 3]; vn[tb][r] = ((r & 1) ? hi_bf(uw) : lo_bf(uw)) - vn[tb][r]; }
;                 vb[tb][0] = pack8(vn[tb], 0); vb[tb][1] = pack8(vn[tb], 1);
;             }
;             __builtin_amdgcn_sched_barrier(0);
;             { const int n1_ = (n + 1 < 128) ? n + 1 : 127; GS_LOADU(n1_); }
;             bf16x8 qop[8];
; #pragma unroll
;             for (int kb = 0; kb < 4; ++kb)
; #pragma unroll
;                 for (int tb2 = 0; tb2 < 2; ++tb2)
; #pragma unroll
;                     for (int c = 0; c < 2; ++c) aop[(kb * 2 + tb2) * 2 + c] = lds_a2(Kt + (kb * 32 + l32) * 68 + tb2 * 32 + c * 16 + hb * 4);
; #pragma unroll
;             for (int kb = 0; kb < 4; ++kb)
; #pragma unroll
;                 for (int r = 0; r < 16; ++r) S[kb][r] *= gl;
;             __builtin_amdgcn_sched_barrier(0);
; #pragma unroll
;             for (int tb2 = 0; tb2 < 2; ++tb2)
; #pragma unroll
;                 for (int c = 0; c < 2; ++c)
; #pragma unroll
;                     for (int kb = 0; kb < 4; ++kb)
;                         S[kb] = __builtin_amdgcn_mfma_f32_32x32x16_bf16(aop[(kb * 2 + tb2) * 2 + c], vb[tb2][c], S[kb], 0, 0, 0);
	v_mfma_f32_32x32x16_bf16 v[80:95], v[208:211], v[140:143], v[80:95]
	v_mul_f32 v72, v72, v187
	v_mul_f32 v73, v73, v187
	v_mul_f32 v74, v74, v187
	v_mul_f32 v75, v75, v187
	s_waitcnt lgkmcnt(0)
	v_mfma_f32_32x32x16_bf16 v[96:111], v[212:215], v[140:143], v[96:111]
	v_mul_f32 v76, v76, v187
	v_mul_f32 v77, v77, v187
	v_mul_f32 v78, v78, v187
	v_mul_f32 v79, v79, v187
	ds_read_b64 v[224:225], v185 offset:33792
	ds_read_b64 v[226:227], v185 offset:33808
	ds_read_b64 v[228:229], v185 offset:38144
	ds_read_b64 v[230:231], v185 offset:38160
	ds_read_b64 v[232:233], v185 offset:42496
	ds_read_b64 v[234:235], v185 offset:42512
	ds_read_b64 v[236:237], v185 offset:46848
	ds_read_b64 v[238:239], v185 offset:46864
	ds_read_b64 v[240:241], v185 offset:33824
	ds_read_b64 v[242:243], v185 offset:33840
	v_cvt_pk_bf16_f32 v146, v80, v81
	v_cvt_pk_bf16_f32 v147, v82, v83
	v_cvt_pk_bf16_f32 v148, v84, v85
	v_cvt_pk_bf16_f32 v149, v86, v87
	v_cvt_pk_bf16_f32 v150, v88, v89
	v_cvt_pk_bf16_f32 v151, v90, v91
	v_cvt_pk_bf16_f32 v152, v92, v93
	v_cvt_pk_bf16_f32 v153, v94, v95
	v_cvt_pk_bf16_f32 v154, v96, v97
	v_cvt_pk_bf16_f32 v155, v98, v99
	v_cvt_pk_bf16_f32 v156, v100, v101
	v_cvt_pk_bf16_f32 v157, v102, v103
	v_cvt_pk_bf16_f32 v158, v104, v105
	v_cvt_pk_bf16_f32 v159, v106, v107
	v_cvt_pk_bf16_f32 v160, v108, v109
	v_cvt_pk_bf16_f32 v161, v110, v111
	ds_write_b128 v189, v[146:149] offset:0
	ds_write_b128 v189, v[150:153] offset:1024
	ds_write_b128 v189, v[154:157] offset:2048
	ds_write_b128 v189, v[158:161] offset:3072
	s_waitcnt lgkmcnt(12)
	v_mfma_f32_32x32x16_bf16 v[16:31], v[224:227], v[146:149], v[16:31]
	ds_read_b64 v[244:245], v185 offset:38176
	ds_read_b64 v[246:247], v185 offset:38192
	s_waitcnt lgkmcnt(12)
	v_mfma_f32_32x32x16_bf16 v[32:47], v[228:231], v[146:149], v[32:47]
	ds_read_b64 v[248:249], v185 offset:42528
	ds_read_b64 v[250:251], v185 offset:42544
	s_waitcnt lgkmcnt(12)
	v_mfma_f32_32x32x16_bf16 v[48:63], v[232:235], v[146:149], v[48:63]
	ds_read_b64 v[224:225], v185 offset:46880
	ds_read_b64 v[226:227], v185 offset:46896
	s_waitcnt lgkmcnt(12)
	v_mfma_f32_32x32x16_bf16 v[64:79], v[236:239], v[146:149], v[64:79]
	ds_read_b64 v[228:229], v185 offset:33856
	ds_read_b64 v[230:231], v185 offset:33872
	s_waitcnt lgkmcnt(12)
	v_mfma_f32_32x32x16_bf16 v[16:31], v[240:243], v[150:153], v[16:31]
	ds_read_b64 v[232:233], v185 offset:38208
	ds_read_b64 v[234:235], v185 offset:38224
	s_waitcnt lgkmcnt(8)
	v_mfma_f32_32x32x16_bf16 v[32:47], v[244:247], v[150:153], v[32:47]
	ds_read_b64 v[236:237], v185 offset:42560
	ds_read_b64 v[238:239], v185 offset:42576
	s_waitcnt lgkmcnt(8)
	v_mfma_f32_32x32x16_bf16 v[48:63], v[248:251], v[150:153], v[48:63]
	ds_read_b64 v[240:241], v185 offset:46912
	ds_read_b64 v[242:243], v185 offset:46928
	s_waitcnt lgkmcnt(8)
	v_mfma_f32_32x32x16_bf16 v[64:79], v[224:227], v[150:153], v[64:79]
	ds_read_b64 v[244:245], v185 offset:33888
	ds_read_b64 v[246:247], v185 offset:33904
	s_waitcnt lgkmcnt(8)
	v_mfma_f32_32x32x16_bf16 v[16:31], v[228:231], v[154:157], v[16:31]
	ds_read_b64 v[248:249], v185 offset:38240
	ds_read_b64 v[250:251], v185 offset:38256
	s_waitcnt lgkmcnt(8)
	v_mfma_f32_32x32x16_bf16 v[32:47], v[232:235], v[154:157], v[32:47]
	ds_read_b64 v[224:225], v185 offset:42592
	ds_read_b64 v[226:227], v185 offset:42608
	s_waitcnt lgkmcnt(8)
	v_mfma_f32_32x32x16_bf16 v[48:63], v[236:239], v[154:157], v[48:63]
	ds_read_b64 v[228:229], v185 offset:46944
	ds_read_b64 v[230:231], v185 offset:46960
	s_waitcnt lgkmcnt(8)
	v_mfma_f32_32x32x16_bf16 v[64:79], v[240:243], v[154:157], v[64:79]
	s_waitcnt lgkmcnt(6)
	v_mfma_f32_32x32x16_bf16 v[16:31], v[244:247], v[158:161], v[16:31]
	s_waitcnt lgkmcnt(4)
	v_mfma_f32_32x32x16_bf16 v[32:47], v[248:251], v[158:161], v[32:47]
	s_waitcnt lgkmcnt(2)
	v_mfma_f32_32x32x16_bf16 v[48:63], v[224:227], v[158:161], v[48:63]
	s_waitcnt lgkmcnt(0)
	v_mfma_f32_32x32x16_bf16 v[64:79], v[228:231], v[158:161], v[64:79]
	s_nop 5
	v_cvt_pk_bf16_f32 v112, -v16, -v17
	v_cvt_pk_bf16_f32 v113, -v18, -v19
	v_cvt_pk_bf16_f32 v114, -v20, -v21
	v_cvt_pk_bf16_f32 v115, -v22, -v23
	v_cvt_pk_bf16_f32 v116, -v24, -v25
	v_cvt_pk_bf16_f32 v117, -v26, -v27
	v_cvt_pk_bf16_f32 v118, -v28, -v29
	v_cvt_pk_bf16_f32 v119, -v30, -v31
	v_cvt_pk_bf16_f32 v120, -v32, -v33
	v_cvt_pk_bf16_f32 v121, -v34, -v35
	v_cvt_pk_bf16_f32 v122, -v36, -v37
	v_cvt_pk_bf16_f32 v123, -v38, -v39
	v_cvt_pk_bf16_f32 v124, -v40, -v41
	v_cvt_pk_bf16_f32 v125, -v42, -v43
	v_cvt_pk_bf16_f32 v126, -v44, -v45
	v_cvt_pk_bf16_f32 v127, -v46, -v47
	v_cvt_pk_bf16_f32 v128, -v48, -v49
	v_cvt_pk_bf16_f32 v129, -v50, -v51
	v_cvt_pk_bf16_f32 v130, -v52, -v53
	v_cvt_pk_bf16_f32 v131, -v54, -v55
	v_cvt_pk_bf16_f32 v132, -v56, -v57
	v_cvt_pk_bf16_f32 v133, -v58, -v59
	v_cvt_pk_bf16_f32 v134, -v60, -v61
	v_cvt_pk_bf16_f32 v135, -v62, -v63
	v_cvt_pk_bf16_f32 v136, -v64, -v65
	v_cvt_pk_bf16_f32 v137, -v66, -v67
	v_cvt_pk_bf16_f32 v138, -v68, -v69
	v_cvt_pk_bf16_f32 v139, -v70, -v71
	v_cvt_pk_bf16_f32 v140, -v72, -v73
	v_cvt_pk_bf16_f32 v141, -v74, -v75
	v_cvt_pk_bf16_f32 v142, -v76, -v77
	v_cvt_pk_bf16_f32 v143, -v78, -v79
	ds_write_b128 v188, v[112:115] offset:0
	ds_write_b128 v188, v[116:119] offset:1024
	ds_write_b128 v188, v[120:123] offset:2048
	ds_write_b128 v188, v[124:127] offset:3072
	ds_write_b128 v188, v[128:131] offset:4096
	ds_write_b128 v188, v[132:135] offset:5120
	ds_write_b128 v188, v[136:139] offset:6144
	ds_write_b128 v188, v[140:143] offset:7168
	s_add_u32 s26, s26, 1
	s_waitcnt lgkmcnt(0)
	v_add_u32 v184, s30, v184
	v_add_u32 v185, s30, v185
	s_sub_u32 s30, 0, s30
	v_subrev_u32 v188, s12, v188
	s_sub_u32 s12, 0, s12
	v_add_u32 v189, s13, v189
	s_sub_u32 s13, 0, s13
	s_barrier
	s_cmp_lt_u32 s26, 0x80
	s_cbranch_scc1 .Lsc0_loop
	s_waitcnt vmcnt(0)
	s_branch .LBB0_156
; __device__ __forceinline__ bf16_t f2bf(float f) { return (bf16_t)(cvt_pk(f, 0.f) & 0xffffu); }
; __device__ __forceinline__ void gdn_scan_item(const Ctx& a, int l, int b, int h, int half, LAS unsigned char* lds, int variant) {
;     ...
; #pragma unroll
;             for (int tb2 = 0; tb2 < 2; ++tb2)
; #pragma unroll
;                 for (int c = 0; c < 2; ++c)
; #pragma unroll
;                     for (int tb = 0; tb < 2; ++tb) qop[(tb2 * 2 + c) * 2 + tb] = lds_a2(QKb + (tb * 32 + l32) * 68 + tb2 * 32 + c * 16 + hb * 4);
;             __builtin_amdgcn_sched_barrier(0);
; #pragma unroll
;             for (int tb2 = 0; tb2 < 2; ++tb2)
; #pragma unroll
;                 for (int c = 0; c < 2; ++c)
; #pragma unroll
;                     for (int tb = 0; tb < 2; ++tb) o[tb] = __builtin_amdgcn_mfma_f32_32x32x16_bf16(qop[(tb2 * 2 + c) * 2 + tb], vb[tb2][c], o[tb], 0, 0, 0);
;             __builtin_amdgcn_sched_barrier(0);
;             {
;                 bf16_t* op = br + ((size_t)b * SEQ + n * 64) * BR + 512 + h * 128 + dv0 + l32;
; #pragma unroll
;                 for (int tb = 0; tb < 2; ++tb)
; #pragma unroll
;                     for (int r = 0; r < 16; ++r) op[(size_t)(tb * 32 + (r >> 2) * 8 + hb * 4 + (r & 3)) * BR] = f2bf(o[tb][r]);
.Lsc1_entry:
	s_lshr_b32 s42, s2, 2
	s_and_b32 s43, s2, 3
	v_readlane_b32 s8, v255, 7
	s_mul_i32 s8, s8, 0xc00
	s_lshl_b32 s12, s42, 8
	s_add_u32 s8, s8, s12
	s_lshl_b32 s12, s43, 6
	s_add_u32 s8, s8, s12
	s_add_u32 s8, s8, 0x400
	s_add_u32 s40, s16, 0x58f4200
	s_addc_u32 s41, s17, 0
	s_add_u32 s40, s40, s8
	s_addc_u32 s41, s41, 0
	v_and_b32 v1, 31, v195
	v_lshrrev_b32 v2, 5, v195
	v_mul_u32_u24 v184, 264, v1
	v_lshl_add_u32 v184, v2, 3, v184
	v_mul_u32_u24 v185, 136, v1
	v_lshl_add_u32 v185, v2, 3, v185
	v_lshlrev_b32 v188, 4, v195
	v_add_u32 v189, 136192, v188
	v_add_u32 v188, 128000, v188
	v_mul_u32_u24 v190, 72, v1
	v_lshl_add_u32 v190, v2, 3, v190
	v_add_u32 v190, 144384, v190
	v_bfe_u32 v3, v195, 2, 2
	v_lshl_add_u32 v3, v2, 4, v3
	v_mul_u32_u24 v191, 72, v3
	v_bfe_u32 v3, v195, 4, 1
	v_lshl_add_u32 v191, v3, 5, v191
	v_and_b32 v4, 3, v195
	v_lshl_add_u32 v191, v4, 3, v191
	v_add_u32 v191, 144384, v191
	v_and_b32 v4, 15, v195
	v_lshl_add_u32 v4, v3, 4, v4
	v_mul_u32_u24 v192, 0xc00, v4
	v_lshl_add_u32 v192, v2, 5, v192
	v_add_u32 v193, 0x18000, v192
	s_mov_b32 s30, 0xea00
	s_movk_i32 s12, 0x2000
	s_movk_i32 s13, 0x1000
	s_mov_b32 s26, 1
	v_mov_b32 v16, 0
	v_mov_b32 v17, 0
	v_mov_b32 v18, 0
	v_mov_b32 v19, 0
	v_mov_b32 v20, 0
	v_mov_b32 v21, 0
	v_mov_b32 v22, 0
	v_mov_b32 v23, 0
	v_mov_b32 v24, 0
	v_mov_b32 v25, 0
	v_mov_b32 v26, 0
	v_mov_b32 v27, 0
	v_mov_b32 v28, 0
	v_mov_b32 v29, 0
	v_mov_b32 v30, 0
	v_mov_b32 v31, 0
	v_mov_b32 v32, 0
	v_mov_b32 v33, 0
	v_mov_b32 v34, 0
	v_mov_b32 v35, 0
	v_mov_b32 v36, 0
	v_mov_b32 v37, 0
	v_mov_b32 v38, 0
	v_mov_b32 v39, 0
	v_mov_b32 v40, 0
	v_mov_b32 v41, 0
	v_mov_b32 v42, 0
	v_mov_b32 v43, 0
	v_mov_b32 v44, 0
	v_mov_b32 v45, 0
	v_mov_b32 v46, 0
	v_mov_b32 v47, 0
	ds_read_b64 v[80:81], v185 offset:51200
	ds_read_b64 v[82:83], v185 offset:51216
	ds_read_b64 v[96:97], v185 offset:55552
	ds_read_b64 v[98:99], v185 offset:55568
	ds_read_b64 v[84:85], v185 offset:51232
	ds_read_b64 v[86:87], v185 offset:51248
	ds_read_b64 v[100:101], v185 offset:55584
	ds_read_b64 v[102:103], v185 offset:55600
	s_waitcnt lgkmcnt(4)
	ds_read_b64 v[88:89], v185 offset:51264
	ds_read_b64 v[90:91], v185 offset:51280
	ds_read_b64 v[104:105], v185 offset:55616
	ds_read_b64 v[106:107], v185 offset:55632
	ds_read_b64 v[92:93], v185 offset:51296
	ds_read_b64 v[94:95], v185 offset:51312
	ds_read_b64 v[108:109], v185 offset:55648
	ds_read_b64 v[110:111], v185 offset:55664
	s_waitcnt lgkmcnt(0)
	v_add_u32 v184, s30, v184
	v_add_u32 v185, s30, v185
	s_sub_u32 s30, 0, s30
	s_barrier
.Lsc1_loop:
	ds_read_b128 v[146:149], v189 offset:0
	ds_read_b128 v[150:153], v189 offset:1024
	ds_read_b128 v[154:157], v189 offset:2048
	ds_read_b128 v[158:161], v189 offset:3072
	s_waitcnt lgkmcnt(3)
	s_nop 6
	v_mfma_f32_32x32x16_bf16 v[48:63], v[80:83], v[146:149], 0
	v_mfma_f32_32x32x16_bf16 v[64:79], v[96:99], v[146:149], 0
	s_waitcnt lgkmcnt(2)
	v_mfma_f32_32x32x16_bf16 v[48:63], v[84:87], v[150:153], v[48:63]
	v_mfma_f32_32x32x16_bf16 v[64:79], v[100:103], v[150:153], v[64:79]
	s_waitcnt lgkmcnt(1)
	v_mfma_f32_32x32x16_bf16 v[48:63], v[88:91], v[154:157], v[48:63]
	v_mfma_f32_32x32x16_bf16 v[64:79], v[104:107], v[154:157], v[64:79]
	s_waitcnt lgkmcnt(0)
	v_mfma_f32_32x32x16_bf16 v[48:63], v[92:95], v[158:161], v[48:63]
	v_mfma_f32_32x32x16_bf16 v[64:79], v[108:111], v[158:161], v[64:79]
	s_nop 7
	s_nop 2
	v_sub_f32 v48, v48, v16
	v_sub_f32 v49, v49, v17
	v_sub_f32 v50, v50, v18
	v_sub_f32 v51, v51, v19
	v_sub_f32 v52, v52, v20
	v_sub_f32 v53, v53, v21
	v_sub_f32 v54, v54, v22
	v_sub_f32 v55, v55, v23
	v_sub_f32 v56, v56, v24
	v_sub_f32 v57, v57, v25
	v_sub_f32 v58, v58, v26
	v_sub_f32 v59, v59, v27
	v_sub_f32 v60, v60, v28
	v_sub_f32 v61, v61, v29
	v_sub_f32 v62, v62, v30
	v_sub_f32 v63, v63, v31
	v_sub_f32 v64, v64, v32
	v_sub_f32 v65, v65, v33
	v_sub_f32 v66, v66, v34
	v_sub_f32 v67, v67, v35
	v_sub_f32 v68, v68, v36
	v_sub_f32 v69, v69, v37
	v_sub_f32 v70, v70, v38
	v_sub_f32 v71, v71, v39
	v_sub_f32 v72, v72, v40
	v_sub_f32 v73, v73, v41
	v_sub_f32 v74, v74, v42
	v_sub_f32 v75, v75, v43
	v_sub_f32 v76, v76, v44
	v_sub_f32 v77, v77, v45
	v_sub_f32 v78, v78, v46
	v_sub_f32 v79, v79, v47
	v_cvt_pk_bf16_f32 v216, v48, v49
	v_cvt_pk_bf16_f32 v217, v50, v51
	ds_write_b64 v190, v[216:217] offset:0
	v_cvt_pk_bf16_f32 v218, v52, v53
	v_cvt_pk_bf16_f32 v219, v54, v55
	ds_write_b64 v190, v[218:219] offset:16
	v_cvt_pk_bf16_f32 v220, v56, v57
	v_cvt_pk_bf16_f32 v221, v58, v59
	ds_write_b64 v190, v[220:221] offset:32
	v_cvt_pk_bf16_f32 v222, v60, v61
	v_cvt_pk_bf16_f32 v223, v62, v63
	ds_write_b64 v190, v[222:223] offset:48
	ds_read_b64_tr_b16 v[162:163], v191 offset:0
	ds_read_b64_tr_b16 v[164:165], v191 offset:288
	ds_read_b64_tr_b16 v[166:167], v191 offset:576
	ds_read_b64_tr_b16 v[168:169], v191 offset:864
	v_cvt_pk_bf16_f32 v224, v64, v65
	v_cvt_pk_bf16_f32 v225, v66, v67
	ds_write_b64 v190, v[224:225] offset:0
	v_cvt_pk_bf16_f32 v226, v68, v69
	v_cvt_pk_bf16_f32 v227, v70, v71
	ds_write_b64 v190, v[226:227] offset:16
	v_cvt_pk_bf16_f32 v228, v72, v73
	v_cvt_pk_bf16_f32 v229, v74, v75
	ds_write_b64 v190, v[228:229] offset:32
	v_cvt_pk_bf16_f32 v230, v76, v77
	v_cvt_pk_bf16_f32 v231, v78, v79
	ds_write_b64 v190, v[230:231] offset:48
	ds_read_b64_tr_b16 v[170:171], v191 offset:0
	ds_read_b64_tr_b16 v[172:173], v191 offset:288
	ds_read_b64_tr_b16 v[174:175], v191 offset:576
	ds_read_b64_tr_b16 v[176:177], v191 offset:864
	s_waitcnt lgkmcnt(10)
	global_store_dwordx4 v192, v[162:165], s[40:41]
	s_waitcnt lgkmcnt(8)
	global_store_dwordx4 v192, v[166:169], s[40:41] offset:16
	s_waitcnt lgkmcnt(2)
	global_store_dwordx4 v193, v[170:173], s[40:41]
	s_waitcnt lgkmcnt(0)
; __device__ __forceinline__ bf16_t f2bf(float f) { return (bf16_t)(cvt_pk(f, 0.f) & 0xffffu); }
; #define GS_BAR() asm volatile("s_waitcnt lgkmcnt(0)\n\ts_barrier" ::: "memory")
; __device__ __forceinline__ void gdn_scan_item(const Ctx& a, int l, int b, int h, int half, LAS unsigned char* lds, int variant) {
;     ...
;             for (int kb = 0; kb < 4; ++kb) {
; #pragma unroll
;                 for (int c = 0; c < 2; ++c)
; #pragma unroll
;                     for (int tb = 0; tb < 2; ++tb) {
;                         aop[c * 2 + tb] = lds_a2(Wb + (tb * 32 + l32) * 132 + kb * 32 + c * 16 + hb * 4);
;                         aop[4 + c * 2 + tb] = lds_a2(Qb + (tb * 32 + l32) * 132 + kb * 32 + c * 16 + hb * 4);
;                     }
;                 __builtin_amdgcn_sched_barrier(0);
; #pragma unroll
;                 for (int c = 0; c < 2; ++c) {
;                     bf16x8 sb = pack8(S[kb], c);
; #pragma unroll
;                     for (int tb = 0; tb < 2; ++tb) {
;                         vn[tb] = __builtin_amdgcn_mfma_f32_32x32x16_bf16(aop[c * 2 + tb], sb, vn[tb], 0, 0, 0);
;                         o[tb] = __builtin_amdgcn_mfma_f32_32x32x16_bf16(aop[4 + c * 2 + tb], sb, o[tb], 0, 0, 0);
;                     }
;                 }
;                 __builtin_amdgcn_sched_barrier(0);
;     ...
;             for (int tb2 = 0; tb2 < 2; ++tb2)
; #pragma unroll
;                 for (int c = 0; c < 2; ++c)
; #pragma unroll
;                     for (int tb = 0; tb < 2; ++tb) qop[(tb2 * 2 + c) * 2 + tb] = lds_a2(QKb + (tb * 32 + l32) * 68 + tb2 * 32 + c * 16 + hb * 4);
;             __builtin_amdgcn_sched_barrier(0);
; #pragma unroll
;             for (int tb2 = 0; tb2 < 2; ++tb2)
; #pragma unroll
;                 for (int c = 0; c < 2; ++c)
; #pragma unroll
;                     for (int tb = 0; tb < 2; ++tb) o[tb] = __builtin_amdgcn_mfma_f32_32x32x16_bf16(qop[(tb2 * 2 + c) * 2 + tb], vb[tb2][c], o[tb], 0, 0, 0);
;             __builtin_amdgcn_sched_barrier(0);
;             {
;                 bf16_t* op = br + ((size_t)b * SEQ + n * 64) * BR + 512 + h * 128 + dv0 + l32;
; #pragma unroll
;                 for (int tb = 0; tb < 2; ++tb)
; #pragma unroll
;                     for (int r = 0; r < 16; ++r) op[(size_t)(tb * 32 + (r >> 2) * 8 + hb * 4 + (r & 3)) * BR] = f2bf(o[tb][r]);
;             }
;             GS_BAR();
	global_store_dwordx4 v193, v[174:177], s[40:41] offset:16
	s_add_u32 s40, s40, 0x30000
	s_addc_u32 s41, s41, 0
	ds_read_b128 v[112:115], v188 offset:0
	ds_read_b128 v[116:119], v188 offset:1024
	ds_read_b128 v[120:123], v188 offset:2048
	ds_read_b128 v[124:127], v188 offset:3072
	ds_read_b128 v[128:131], v188 offset:4096
	ds_read_b128 v[132:135], v188 offset:5120
	ds_read_b128 v[136:139], v188 offset:6144
	ds_read_b128 v[140:143], v188 offset:7168
	ds_read_b64 v[200:201], v184 offset:16896
	ds_read_b64 v[202:203], v184 offset:16912
	ds_read_b64 v[204:205], v184 offset:25344
	ds_read_b64 v[206:207], v184 offset:25360
	ds_read_b64 v[208:209], v184 offset:16928
	ds_read_b64 v[210:211], v184 offset:16944
	s_waitcnt lgkmcnt(4)
	v_mfma_f32_32x32x16_bf16 v[16:31], v[200:203], v[112:115], 0
	ds_read_b64 v[212:213], v184 offset:25376
	ds_read_b64 v[214:215], v184 offset:25392
	s_waitcnt lgkmcnt(4)
	v_mfma_f32_32x32x16_bf16 v[32:47], v[204:207], v[112:115], 0
	ds_read_b64 v[216:217], v184 offset:16960
	ds_read_b64 v[218:219], v184 offset:16976
	s_waitcnt lgkmcnt(4)
	v_mfma_f32_32x32x16_bf16 v[16:31], v[208:211], v[116:119], v[16:31]
	ds_read_b64 v[220:221], v184 offset:25408
	ds_read_b64 v[222:223], v184 offset:25424
	s_waitcnt lgkmcnt(4)
	v_mfma_f32_32x32x16_bf16 v[32:47], v[212:215], v[116:119], v[32:47]
	ds_read_b64 v[224:225], v184 offset:16992
	ds_read_b64 v[226:227], v184 offset:17008
	s_waitcnt lgkmcnt(4)
	v_mfma_f32_32x32x16_bf16 v[16:31], v[216:219], v[120:123], v[16:31]
	ds_read_b64 v[228:229], v184 offset:25440
	ds_read_b64 v[230:231], v184 offset:25456
	s_waitcnt lgkmcnt(4)
	v_mfma_f32_32x32x16_bf16 v[32:47], v[220:223], v[120:123], v[32:47]
	ds_read_b64 v[200:201], v184 offset:17024
	ds_read_b64 v[202:203], v184 offset:17040
	s_waitcnt lgkmcnt(4)
	v_mfma_f32_32x32x16_bf16 v[16:31], v[224:227], v[124:127], v[16:31]
	ds_read_b64 v[204:205], v184 offset:25472
	ds_read_b64 v[206:207], v184 offset:25488
	s_waitcnt lgkmcnt(4)
	v_mfma_f32_32x32x16_bf16 v[32:47], v[228:231], v[124:127], v[32:47]
	ds_read_b64 v[208:209], v184 offset:17056
	ds_read_b64 v[210:211], v184 offset:17072
	s_waitcnt lgkmcnt(4)
	v_mfma_f32_32x32x16_bf16 v[16:31], v[200:203], v[128:131], v[16:31]
	ds_read_b64 v[212:213], v184 offset:25504
	ds_read_b64 v[214:215], v184 offset:25520
	s_waitcnt lgkmcnt(4)
	v_mfma_f32_32x32x16_bf16 v[32:47], v[204:207], v[128:131], v[32:47]
	ds_read_b64 v[216:217], v184 offset:17088
	ds_read_b64 v[218:219], v184 offset:17104
	s_waitcnt lgkmcnt(4)
	v_mfma_f32_32x32x16_bf16 v[16:31], v[208:211], v[132:135], v[16:31]
	ds_read_b64 v[220:221], v184 offset:25536
	ds_read_b64 v[222:223], v184 offset:25552
	s_waitcnt lgkmcnt(4)
	v_mfma_f32_32x32x16_bf16 v[32:47], v[212:215], v[132:135], v[32:47]
	ds_read_b64 v[224:225], v184 offset:17120
	ds_read_b64 v[226:227], v184 offset:17136
	s_waitcnt lgkmcnt(4)
	v_mfma_f32_32x32x16_bf16 v[16:31], v[216:219], v[136:139], v[16:31]
	ds_read_b64 v[228:229], v184 offset:25568
	ds_read_b64 v[230:231], v184 offset:25584
	s_waitcnt lgkmcnt(4)
	v_mfma_f32_32x32x16_bf16 v[32:47], v[220:223], v[136:139], v[32:47]
	s_waitcnt lgkmcnt(2)
	v_mfma_f32_32x32x16_bf16 v[16:31], v[224:227], v[140:143], v[16:31]
	s_waitcnt lgkmcnt(0)
	v_mfma_f32_32x32x16_bf16 v[32:47], v[228:231], v[140:143], v[32:47]
	ds_read_b64 v[80:81], v185 offset:51200
	ds_read_b64 v[82:83], v185 offset:51216
	ds_read_b64 v[96:97], v185 offset:55552
	ds_read_b64 v[98:99], v185 offset:55568
	ds_read_b64 v[84:85], v185 offset:51232
	ds_read_b64 v[86:87], v185 offset:51248
	ds_read_b64 v[100:101], v185 offset:55584
	ds_read_b64 v[102:103], v185 offset:55600
	s_waitcnt lgkmcnt(4)
	ds_read_b64 v[88:89], v185 offset:51264
	ds_read_b64 v[90:91], v185 offset:51280
	ds_read_b64 v[104:105], v185 offset:55616
	ds_read_b64 v[106:107], v185 offset:55632
	ds_read_b64 v[92:93], v185 offset:51296
	ds_read_b64 v[94:95], v185 offset:51312
	ds_read_b64 v[108:109], v185 offset:55648
	ds_read_b64 v[110:111], v185 offset:55664
	s_waitcnt lgkmcnt(0)
	v_add_u32 v184, s30, v184
	v_add_u32 v185, s30, v185
	s_sub_u32 s30, 0, s30
	v_subrev_u32 v188, s12, v188
	s_sub_u32 s12, 0, s12
	v_add_u32 v189, s13, v189
	s_sub_u32 s13, 0, s13
	s_barrier
; __device__ __forceinline__ bf16_t f2bf(float f) { return (bf16_t)(cvt_pk(f, 0.f) & 0xffffu); }
; #define GS_BAR() asm volatile("s_waitcnt lgkmcnt(0)\n\ts_barrier" ::: "memory")
; __device__ __forceinline__ void gdn_scan_item(const Ctx& a, int l, int b, int h, int half, LAS unsigned char* lds, int variant) {
;     ...
;             for (int tb2 = 0; tb2 < 2; ++tb2)
; #pragma unroll
;                 for (int c = 0; c < 2; ++c)
; #pragma unroll
;                     for (int tb = 0; tb < 2; ++tb) o[tb] = __builtin_amdgcn_mfma_f32_32x32x16_bf16(qop[(tb2 * 2 + c) * 2 + tb], vb[tb2][c], o[tb], 0, 0, 0);
;             __builtin_amdgcn_sched_barrier(0);
;             {
;                 bf16_t* op = br + ((size_t)b * SEQ + n * 64) * BR + 512 + h * 128 + dv0 + l32;
; #pragma unroll
;                 for (int tb = 0; tb < 2; ++tb)
; #pragma unroll
;                     for (int r = 0; r < 16; ++r) op[(size_t)(tb * 32 + (r >> 2) * 8 + hb * 4 + (r & 3)) * BR] = f2bf(o[tb][r]);
;             }
;             GS_BAR();
	s_add_u32 s26, s26, 1
	s_cmp_lt_u32 s26, 0x80
	s_cbranch_scc1 .Lsc1_loop
	ds_read_b128 v[146:149], v189 offset:0
	ds_read_b128 v[150:153], v189 offset:1024
	ds_read_b128 v[154:157], v189 offset:2048
	ds_read_b128 v[158:161], v189 offset:3072
	s_waitcnt lgkmcnt(3)
	v_mfma_f32_32x32x16_bf16 v[48:63], v[80:83], v[146:149], 0
	v_mfma_f32_32x32x16_bf16 v[64:79], v[96:99], v[146:149], 0
	s_waitcnt lgkmcnt(2)
	v_mfma_f32_32x32x16_bf16 v[48:63], v[84:87], v[150:153], v[48:63]
	v_mfma_f32_32x32x16_bf16 v[64:79], v[100:103], v[150:153], v[64:79]
	s_waitcnt lgkmcnt(1)
	v_mfma_f32_32x32x16_bf16 v[48:63], v[88:91], v[154:157], v[48:63]
	v_mfma_f32_32x32x16_bf16 v[64:79], v[104:107], v[154:157], v[64:79]
	s_waitcnt lgkmcnt(0)
	v_mfma_f32_32x32x16_bf16 v[48:63], v[92:95], v[158:161], v[48:63]
	v_mfma_f32_32x32x16_bf16 v[64:79], v[108:111], v[158:161], v[64:79]
	s_nop 7
	s_nop 2
	v_sub_f32 v48, v48, v16
	v_sub_f32 v49, v49, v17
	v_sub_f32 v50, v50, v18
	v_sub_f32 v51, v51, v19
	v_sub_f32 v52, v52, v20
	v_sub_f32 v53, v53, v21
	v_sub_f32 v54, v54, v22
	v_sub_f32 v55, v55, v23
	v_sub_f32 v56, v56, v24
	v_sub_f32 v57, v57, v25
	v_sub_f32 v58, v58, v26
	v_sub_f32 v59, v59, v27
	v_sub_f32 v60, v60, v28
	v_sub_f32 v61, v61, v29
	v_sub_f32 v62, v62, v30
	v_sub_f32 v63, v63, v31
	v_sub_f32 v64, v64, v32
	v_sub_f32 v65, v65, v33
	v_sub_f32 v66, v66, v34
	v_sub_f32 v67, v67, v35
	v_sub_f32 v68, v68, v36
	v_sub_f32 v69, v69, v37
	v_sub_f32 v70, v70, v38
	v_sub_f32 v71, v71, v39
	v_sub_f32 v72, v72, v40
	v_sub_f32 v73, v73, v41
	v_sub_f32 v74, v74, v42
	v_sub_f32 v75, v75, v43
	v_sub_f32 v76, v76, v44
	v_sub_f32 v77, v77, v45
	v_sub_f32 v78, v78, v46
	v_sub_f32 v79, v79, v47
	v_cvt_pk_bf16_f32 v216, v48, v49
	v_cvt_pk_bf16_f32 v217, v50, v51
	ds_write_b64 v190, v[216:217] offset:0
	v_cvt_pk_bf16_f32 v218, v52, v53
	v_cvt_pk_bf16_f32 v219, v54, v55
	ds_write_b64 v190, v[218:219] offset:16
	v_cvt_pk_bf16_f32 v220, v56, v57
	v_cvt_pk_bf16_f32 v221, v58, v59
	ds_write_b64 v190, v[220:221] offset:32
	v_cvt_pk_bf16_f32 v222, v60, v61
	v_cvt_pk_bf16_f32 v223, v62, v63
	ds_write_b64 v190, v[222:223] offset:48
	ds_read_b64_tr_b16 v[162:163], v191 offset:0
	ds_read_b64_tr_b16 v[164:165], v191 offset:288
	ds_read_b64_tr_b16 v[166:167], v191 offset:576
	ds_read_b64_tr_b16 v[168:169], v191 offset:864
	v_cvt_pk_bf16_f32 v224, v64, v65
	v_cvt_pk_bf16_f32 v225, v66, v67
	ds_write_b64 v190, v[224:225] offset:0
	v_cvt_pk_bf16_f32 v226, v68, v69
	v_cvt_pk_bf16_f32 v227, v70, v71
	ds_write_b64 v190, v[226:227] offset:16
	v_cvt_pk_bf16_f32 v228, v72, v73
	v_cvt_pk_bf16_f32 v229, v74, v75
	ds_write_b64 v190, v[228:229] offset:32
	v_cvt_pk_bf16_f32 v230, v76, v77
	v_cvt_pk_bf16_f32 v231, v78, v79
	ds_write_b64 v190, v[230:231] offset:48
	ds_read_b64_tr_b16 v[170:171], v191 offset:0
	ds_read_b64_tr_b16 v[172:173], v191 offset:288
	ds_read_b64_tr_b16 v[174:175], v191 offset:576
	ds_read_b64_tr_b16 v[176:177], v191 offset:864
	s_waitcnt lgkmcnt(10)
	global_store_dwordx4 v192, v[162:165], s[40:41]
	s_waitcnt lgkmcnt(8)
	global_store_dwordx4 v192, v[166:169], s[40:41] offset:16
	s_waitcnt lgkmcnt(2)
	global_store_dwordx4 v193, v[170:173], s[40:41]
	s_waitcnt lgkmcnt(0)
	global_store_dwordx4 v193, v[174:177], s[40:41] offset:16
	s_add_u32 s40, s40, 0x30000
	s_addc_u32 s41, s41, 0
	s_waitcnt lgkmcnt(0)
	s_branch .LBB0_156

; #define LAS __attribute__((address_space(3)))
; template <int TYPE>
; __device__ __forceinline__ void attn_item(const Ctx& a, int b, int h, int qt, LAS unsigned char* lds) {
;     ...
;     const int qrow = qt * 256 + wv * 32 + l32;
;     bf16x8 Q[NKK];
;     {
;         const bf16_t* qp = TYPE == 0 ? mr + (size_t)qrow * MR + h * 96 : pa + (size_t)qrow * PA + C_MQ + h * 64;
; #pragma unroll
;         for (int kk = 0; kk < NKK; ++kk) Q[kk] = *(const bf16x8*)(qp + kk * 16 + hb * 8);
;     }
;     unsigned qmask = 0xffffffffu;
;     if (TYPE == 1) qmask = ((const unsigned*)(a.ws + WS_MASK))[(size_t)h * SEQ + qrow];
;     f32x16 oacc[2];
; #pragma unroll
;     for (int db = 0; db < 2; ++db)
; #pragma unroll
;         for (int r = 0; r < 16; ++r) oacc[db][r] = 0.f;
;     float mrun = 0.f, lrun = 0.f;
;     const int npair = (qt + 1) * 2;
;     u32x4 kreg[NKC], vreg[2];
;     ...
;     AT_LOAD(0); AT_STORE(0);
;     __syncthreads();
;     for (int kp = 0; kp < npair; ++kp) {
;         const int bufi = kp & 1;
;         if (kp + 1 < npair) AT_LOAD(kp + 1);
;     ...
;         for (int kk = 0; kk < NKK; ++kk)
; #pragma unroll
;             for (int sub = 0; sub < 2; ++sub)
;                 if (act[sub]) {
; #pragma unroll
;                     for (int kb = 0; kb < 2; ++kb) {
;                         bf16x8 ka = *(const LAS bf16x8*)(Kt + (sub * 64 + kb * 32 + l32) * KLD + kk * 16 + hb * 8);
;                         s[sub][kb] = __builtin_amdgcn_mfma_f32_32x32x16_bf16(ka, Q[kk], s[sub][kb], 0, 0, 0);
;                     }
;                 }
.Lat0_entry:
	s_lshr_b32 s47, s12, 4
	s_sub_u32 s47, 31, s47
	s_and_b32 s50, s12, 7
	v_lshrrev_b32 v1, 6, v179
	s_add_u32 s30, s47, 1
	s_lshl_b32 s30, s30, 1
	v_readfirstlane_b32 s51, v1
	v_and_b32 v14, 31, v195
	v_lshrrev_b32 v15, 5, v195
	s_lshl_b32 s8, s47, 8
	s_lshl_b32 s9, s51, 5
	s_add_u32 s8, s8, s9
	v_add_u32 v144, s8, v14
	v_add_u32 v208, s9, v14
	v_lshlrev_b32 v181, 2, v15
	v_sub_u32 v208, v208, v181
	s_mul_i32 s9, s50, 0xc0
	s_add_u32 s56, s16, 0xc8f4200
	s_addc_u32 s57, s17, 0
	s_add_u32 s56, s56, s9
	s_addc_u32 s57, s57, 0
	s_movk_i32 s8, 0xe00
	v_mul_lo_u32 v181, v144, s8
	v_lshl_add_u32 v181, v15, 4, v181
	global_load_dwordx4 v[112:115], v181, s[56:57] offset:0
	global_load_dwordx4 v[116:119], v181, s[56:57] offset:32
	global_load_dwordx4 v[120:123], v181, s[56:57] offset:64
	global_load_dwordx4 v[124:127], v181, s[56:57] offset:96
	global_load_dwordx4 v[128:131], v181, s[56:57] offset:128
	global_load_dwordx4 v[132:135], v181, s[56:57] offset:160
	v_lshrrev_b32 v181, 3, v179
	v_and_b32 v212, 7, v179
	s_lshl_b32 s9, s50, 8
	s_add_u32 s52, s16, 0xc8f4800
	s_addc_u32 s53, s17, 0
	s_add_u32 s52, s52, s9
	s_addc_u32 s53, s53, 0
	s_lshl_b32 s9, s50, 6
	s_add_u32 s54, s16, 0xe4f4200
	s_addc_u32 s55, s17, 0
	s_add_u32 s54, s54, s9
	s_addc_u32 s55, s55, 0
	v_mul_u32_u24 v184, 0xe00, v181
	v_lshl_add_u32 v184, v212, 4, v184
	v_add_u32 v185, 0x38000, v184
	v_lshrrev_b32 v1, 2, v179
	v_and_b32 v188, 3, v179
	v_lshlrev_b32 v186, 9, v1
	v_lshl_add_u32 v186, v188, 4, v186
	v_mul_u32_u24 v201, 0xd0, v1
	v_lshl_add_u32 v201, v188, 4, v201
	v_add_u32 v201, 0x80, v201
	v_mul_u32_u24 v190, 208, v14
	v_lshl_add_u32 v190, v15, 4, v190
	v_mul_u32_u24 v193, 208, v181
	v_lshl_add_u32 v193, v212, 4, v193
	v_and_b32 v1, 2, v181
	v_lshlrev_b32 v1, 5, v1
	v_lshlrev_b32 v188, 4, v212
	v_xor_b32 v1, v1, v188
	v_lshl_add_u32 v200, v181, 7, v1
	v_add_u32 v200, 26624, v200
	v_bfe_u32 v1, v195, 2, 2
	v_lshlrev_b32 v191, 7, v1
	v_bfe_u32 v1, v195, 3, 1
	v_lshl_add_u32 v191, v1, 6, v191
	v_bfe_u32 v1, v195, 4, 1
	v_lshl_add_u32 v191, v1, 5, v191
	v_and_b32 v1, 3, v195
	v_lshl_add_u32 v191, v1, 3, v191
	v_lshl_add_u32 v191, v15, 9, v191
	v_add_u32 v191, 26624, v191
	v_xor_b32 v192, 64, v191
	global_load_dwordx4 v[2:5], v184, s[52:53]
	global_load_dwordx4 v[6:9], v184, s[52:53] offset:128
	global_load_dwordx4 v[10:13], v185, s[52:53]
	global_load_dwordx4 v[136:139], v185, s[52:53] offset:128
	global_load_dwordx4 v[140:143], v186, s[54:55]
	s_add_u32 s52, s52, 0x70000
	s_addc_u32 s53, s53, 0
	s_add_u32 s54, s54, 0x10000
	s_addc_u32 s55, s55, 0
	v_mov_b32 v16, 0
	v_mov_b32 v17, 0
	v_mov_b32 v18, 0
	v_mov_b32 v19, 0
	v_mov_b32 v20, 0
	v_mov_b32 v21, 0
	v_mov_b32 v22, 0
	v_mov_b32 v23, 0
	v_mov_b32 v24, 0
	v_mov_b32 v25, 0
	v_mov_b32 v26, 0
	v_mov_b32 v27, 0
	v_mov_b32 v28, 0
	v_mov_b32 v29, 0
	v_mov_b32 v30, 0
	v_mov_b32 v31, 0
	v_mov_b32 v32, 0
	v_mov_b32 v33, 0
	v_mov_b32 v34, 0
	v_mov_b32 v35, 0
	v_mov_b32 v36, 0
	v_mov_b32 v37, 0
	v_mov_b32 v38, 0
	v_mov_b32 v39, 0
	v_mov_b32 v40, 0
	v_mov_b32 v41, 0
	v_mov_b32 v42, 0
	v_mov_b32 v43, 0
	v_mov_b32 v44, 0
	v_mov_b32 v45, 0
	v_mov_b32 v46, 0
	v_mov_b32 v47, 0
	v_mov_b32 v205, 0
	v_mov_b32 v206, 0
	v_mov_b32 v207, 0x41000000
	s_mov_b64 s[36:37], 0
	s_mov_b32 s26, 0
	s_waitcnt vmcnt(0)
	ds_write_b128 v193, v[2:5]
	ds_write_b128 v193, v[10:13] offset:13312
	ds_write_b128 v200, v[6:9]
	ds_write_b128 v200, v[136:139] offset:8192
	ds_write_b128 v201, v[140:143]
	s_waitcnt lgkmcnt(0)
	global_load_dwordx4 v[2:5], v184, s[52:53]
	global_load_dwordx4 v[6:9], v184, s[52:53] offset:128
	global_load_dwordx4 v[10:13], v185, s[52:53]
	global_load_dwordx4 v[136:139], v185, s[52:53] offset:128
	global_load_dwordx4 v[140:143], v186, s[54:55]
	s_add_u32 s52, s52, 0x70000
	s_addc_u32 s53, s53, 0
	s_add_u32 s54, s54, 0x10000
	s_addc_u32 s55, s55, 0
	s_mov_b32 s8, 0xa800
	v_add_u32 v193, s8, v193
	v_add_u32 v200, s8, v200
	v_add_u32 v201, s8, v201
	s_mov_b32 s12, 0
	s_mov_b32 s13, 1
	s_waitcnt lgkmcnt(0)
	s_barrier
.Lat0_loop:
	s_add_u32 s8, s26, 2
	s_cmp_ge_u32 s8, s30
	s_cselect_b32 s57, 1, 0
	s_cmp_eq_u32 s57, 1
	s_cbranch_scc1 .Lat0_gen
	s_cmp_lg_u64 s[36:37], 0
	s_cbranch_scc1 .Lat0_gen
	v_mov_b32 v211, v0
	ds_read_b128 v[146:149], v190 offset:0
	ds_read_b128 v[150:153], v190 offset:6656
	ds_read_b128 v[154:157], v190 offset:32
	ds_read_b128 v[158:161], v190 offset:6688
	ds_read_b128 v[162:165], v190 offset:64
	ds_read_b128 v[166:169], v190 offset:6720
	s_waitcnt lgkmcnt(5)
	v_mfma_f32_32x32x16_bf16 v[48:63], v[146:149], v[112:115], 0
	ds_read_b128 v[170:173], v190 offset:96
	s_waitcnt lgkmcnt(5)
	v_mfma_f32_32x32x16_bf16 v[64:79], v[150:153], v[112:115], 0
	ds_read_b128 v[174:177], v190 offset:6752
	s_waitcnt lgkmcnt(5)
	v_mfma_f32_32x32x16_bf16 v[48:63], v[154:157], v[116:119], v[48:63]
	ds_read_b128 v[146:149], v190 offset:128
	s_waitcnt lgkmcnt(5)
	v_mfma_f32_32x32x16_bf16 v[64:79], v[158:161], v[116:119], v[64:79]
	ds_read_b128 v[150:153], v190 offset:6784
	s_waitcnt lgkmcnt(5)
	v_mfma_f32_32x32x16_bf16 v[48:63], v[162:165], v[120:123], v[48:63]
	ds_read_b128 v[154:157], v190 offset:160
	s_waitcnt lgkmcnt(5)
	v_mfma_f32_32x32x16_bf16 v[64:79], v[166:169], v[120:123], v[64:79]
	ds_read_b128 v[158:161], v190 offset:6816
	s_waitcnt lgkmcnt(5)
	v_mfma_f32_32x32x16_bf16 v[48:63], v[170:173], v[124:127], v[48:63]
	ds_read_b128 v[162:165], v190 offset:13312
	s_waitcnt lgkmcnt(5)
	v_mfma_f32_32x32x16_bf16 v[64:79], v[174:177], v[124:127], v[64:79]
	ds_read_b128 v[166:169], v190 offset:19968
	s_waitcnt lgkmcnt(5)
	v_mfma_f32_32x32x16_bf16 v[48:63], v[146:149], v[128:131], v[48:63]
	ds_read_b128 v[170:173], v190 offset:13344
	s_waitcnt lgkmcnt(5)
; #define LAS __attribute__((address_space(3)))
; template <int TYPE>
; __device__ __forceinline__ void attn_item(const Ctx& a, int b, int h, int qt, LAS unsigned char* lds) {
;     ...
;         for (int kk = 0; kk < NKK; ++kk)
; #pragma unroll
;             for (int sub = 0; sub < 2; ++sub)
;                 if (act[sub]) {
; #pragma unroll
;                     for (int kb = 0; kb < 2; ++kb) {
;                         bf16x8 ka = *(const LAS bf16x8*)(Kt + (sub * 64 + kb * 32 + l32) * KLD + kk * 16 + hb * 8);
;                         s[sub][kb] = __builtin_amdgcn_mfma_f32_32x32x16_bf16(ka, Q[kk], s[sub][kb], 0, 0, 0);
;                     }
;                 }
;     ...
;             float ps = 0.f;
; #pragma unroll
;             for (int kb = 0; kb < 2; ++kb)
; #pragma unroll
;                 for (int r = 0; r < 16; ++r) { float p = __builtin_amdgcn_exp2f(s[sub][kb][r]); s[sub][kb][r] = p; ps += p; }
;             lrun += ps;
; #pragma unroll
;             for (int kb = 0; kb < 2; ++kb)
; #pragma unroll
;                 for (int c = 0; c < 2; ++c) {
;                     bf16x8 pb = pack8(s[sub][kb], c);
; #pragma unroll
;                     for (int db = 0; db < 2; ++db)
;                         oacc[db] = __builtin_amdgcn_mfma_f32_32x32x16_bf16(lds_a2(VT + (db * 32 + l32) * VLD + sub * 64 + kb * 32 + c * 16 + hb * 4), pb, oacc[db], 0, 0, 0);
;                 }
;             if (rare) {
;                 lrun *= fpost;
; #pragma unroll
;                 for (int db = 0; db < 2; ++db)
; #pragma unroll
;                     for (int r = 0; r < 16; ++r) oacc[db][r] *= fpost;
;             }
;         }
;         if (kp + 1 < npair) AT_STORE(bufi ^ 1);
;         __syncthreads();
	v_mfma_f32_32x32x16_bf16 v[64:79], v[150:153], v[128:131], v[64:79]
	ds_read_b128 v[174:177], v190 offset:20000
	s_waitcnt lgkmcnt(5)
	v_mfma_f32_32x32x16_bf16 v[48:63], v[154:157], v[132:135], v[48:63]
	ds_read_b128 v[146:149], v190 offset:13376
	s_waitcnt lgkmcnt(5)
	v_mfma_f32_32x32x16_bf16 v[64:79], v[158:161], v[132:135], v[64:79]
	ds_read_b128 v[150:153], v190 offset:20032
	s_waitcnt lgkmcnt(5)
	v_mfma_f32_32x32x16_bf16 v[80:95], v[162:165], v[112:115], 0
	ds_read_b128 v[154:157], v190 offset:13408
	s_nop 4
	v_max3_f32 v211, v211, v48, v49
	v_exp_f32 v48, v48
	v_exp_f32 v49, v49
	v_max3_f32 v211, v211, v50, v51
	v_exp_f32 v50, v50
	v_exp_f32 v51, v51
	v_add_f32 v188, v48, v49
	v_cvt_pk_bf16_f32 v48, v48, v49
	s_waitcnt lgkmcnt(5)
	v_mfma_f32_32x32x16_bf16 v[96:111], v[166:169], v[112:115], 0
	ds_read_b128 v[158:161], v190 offset:20064
	v_max3_f32 v211, v211, v52, v53
	v_exp_f32 v52, v52
	v_exp_f32 v53, v53
	v_add_f32 v188, v188, v50
	v_add_f32 v188, v188, v51
	v_cvt_pk_bf16_f32 v49, v50, v51
	v_max3_f32 v211, v211, v54, v55
	v_exp_f32 v54, v54
	s_waitcnt lgkmcnt(5)
	v_mfma_f32_32x32x16_bf16 v[80:95], v[170:173], v[116:119], v[80:95]
	ds_read_b128 v[162:165], v190 offset:13440
	v_exp_f32 v55, v55
	v_add_f32 v188, v188, v52
	v_add_f32 v188, v188, v53
	v_cvt_pk_bf16_f32 v50, v52, v53
	v_max3_f32 v211, v211, v56, v57
	v_exp_f32 v56, v56
	v_exp_f32 v57, v57
	v_add_f32 v188, v188, v54
	s_waitcnt lgkmcnt(5)
	v_mfma_f32_32x32x16_bf16 v[96:111], v[174:177], v[116:119], v[96:111]
	ds_read_b128 v[166:169], v190 offset:20096
	v_add_f32 v188, v188, v55
	v_cvt_pk_bf16_f32 v51, v54, v55
	v_max3_f32 v211, v211, v58, v59
	v_exp_f32 v58, v58
	v_exp_f32 v59, v59
	v_add_f32 v188, v188, v56
	v_add_f32 v188, v188, v57
	v_cvt_pk_bf16_f32 v52, v56, v57
	s_waitcnt lgkmcnt(5)
	v_mfma_f32_32x32x16_bf16 v[80:95], v[146:149], v[120:123], v[80:95]
	ds_read_b128 v[170:173], v190 offset:13472
	v_max3_f32 v211, v211, v60, v61
	v_exp_f32 v60, v60
	v_exp_f32 v61, v61
	v_add_f32 v188, v188, v58
	v_add_f32 v188, v188, v59
	v_cvt_pk_bf16_f32 v53, v58, v59
	v_max3_f32 v211, v211, v62, v63
	v_exp_f32 v62, v62
	s_waitcnt lgkmcnt(5)
	v_mfma_f32_32x32x16_bf16 v[96:111], v[150:153], v[120:123], v[96:111]
	ds_read_b128 v[174:177], v190 offset:20128
	v_exp_f32 v63, v63
	v_add_f32 v188, v188, v60
	v_add_f32 v188, v188, v61
	v_cvt_pk_bf16_f32 v54, v60, v61
	v_add_f32 v188, v188, v62
	v_add_f32 v188, v188, v63
	v_cvt_pk_bf16_f32 v55, v62, v63
	v_max3_f32 v211, v211, v64, v65
	s_waitcnt lgkmcnt(5)
	v_mfma_f32_32x32x16_bf16 v[80:95], v[154:157], v[124:127], v[80:95]
	ds_read_b64_tr_b16 v[146:147], v191 offset:0
	ds_read_b64_tr_b16 v[148:149], v191 offset:1024
	v_exp_f32 v64, v64
	v_exp_f32 v65, v65
	v_max3_f32 v211, v211, v66, v67
	v_exp_f32 v66, v66
	v_exp_f32 v67, v67
	v_add_f32 v188, v188, v64
	v_add_f32 v188, v188, v65
	v_cvt_pk_bf16_f32 v64, v64, v65
	s_waitcnt lgkmcnt(6)
	v_mfma_f32_32x32x16_bf16 v[96:111], v[158:161], v[124:127], v[96:111]
	ds_read_b64_tr_b16 v[150:151], v192 offset:0
	ds_read_b64_tr_b16 v[152:153], v192 offset:1024
	v_max3_f32 v211, v211, v68, v69
	v_exp_f32 v68, v68
	v_exp_f32 v69, v69
	v_add_f32 v188, v188, v66
	v_add_f32 v188, v188, v67
	v_cvt_pk_bf16_f32 v65, v66, v67
	v_max3_f32 v211, v211, v70, v71
	v_exp_f32 v70, v70
	s_waitcnt lgkmcnt(7)
	v_mfma_f32_32x32x16_bf16 v[80:95], v[162:165], v[128:131], v[80:95]
	ds_read_b64_tr_b16 v[154:155], v191 offset:2048
	ds_read_b64_tr_b16 v[156:157], v191 offset:3072
	v_exp_f32 v71, v71
	v_add_f32 v188, v188, v68
	v_add_f32 v188, v188, v69
	v_cvt_pk_bf16_f32 v66, v68, v69
	v_max3_f32 v211, v211, v72, v73
	v_exp_f32 v72, v72
	v_exp_f32 v73, v73
	v_add_f32 v188, v188, v70
	s_waitcnt lgkmcnt(8)
	v_mfma_f32_32x32x16_bf16 v[96:111], v[166:169], v[128:131], v[96:111]
	ds_read_b64_tr_b16 v[158:159], v192 offset:2048
	ds_read_b64_tr_b16 v[160:161], v192 offset:3072
	v_add_f32 v188, v188, v71
	v_cvt_pk_bf16_f32 v67, v70, v71
	v_max3_f32 v211, v211, v74, v75
	v_exp_f32 v74, v74
	v_exp_f32 v75, v75
	v_add_f32 v188, v188, v72
	v_add_f32 v188, v188, v73
	v_cvt_pk_bf16_f32 v68, v72, v73
	s_waitcnt lgkmcnt(9)
	v_mfma_f32_32x32x16_bf16 v[80:95], v[170:173], v[132:135], v[80:95]
	ds_read_b64_tr_b16 v[162:163], v191 offset:4096
	ds_read_b64_tr_b16 v[164:165], v191 offset:5120
	v_max3_f32 v211, v211, v76, v77
	v_exp_f32 v76, v76
	v_exp_f32 v77, v77
	v_add_f32 v188, v188, v74
	v_add_f32 v188, v188, v75
	v_cvt_pk_bf16_f32 v69, v74, v75
	v_max3_f32 v211, v211, v78, v79
	v_exp_f32 v78, v78
	s_waitcnt lgkmcnt(10)
	v_mfma_f32_32x32x16_bf16 v[96:111], v[174:177], v[132:135], v[96:111]
	ds_read_b64_tr_b16 v[166:167], v192 offset:4096
	ds_read_b64_tr_b16 v[168:169], v192 offset:5120
	v_exp_f32 v79, v79
	v_add_f32 v188, v188, v76
	v_add_f32 v188, v188, v77
	v_cvt_pk_bf16_f32 v70, v76, v77
	v_add_f32 v188, v188, v78
	v_add_f32 v188, v188, v79
	v_cvt_pk_bf16_f32 v71, v78, v79
	v_add_f32 v206, v206, v188
	s_waitcnt vmcnt(0)
	ds_write_b128 v193, v[2:5]
	ds_write_b128 v193, v[10:13] offset:13312
	ds_write_b128 v200, v[6:9]
	ds_write_b128 v200, v[136:139] offset:8192
	ds_write_b128 v201, v[140:143]
	s_cmp_eq_u32 s13, 2
	s_cselect_b32 s8, 0x1f800, 0
	s_sub_u32 s8, 0xa800, s8
	s_add_u32 s13, s13, 1
	s_cmp_eq_u32 s13, 3
	s_cselect_b32 s13, 0, s13
	s_waitcnt lgkmcnt(0)
	s_add_u32 s9, s26, 2
	s_cmp_lt_u32 s9, s30
	s_cbranch_scc0 .Lat0_mid1
	global_load_dwordx4 v[2:5], v184, s[52:53]
	global_load_dwordx4 v[6:9], v184, s[52:53] offset:128
	global_load_dwordx4 v[10:13], v185, s[52:53]
	global_load_dwordx4 v[136:139], v185, s[52:53] offset:128
	global_load_dwordx4 v[140:143], v186, s[54:55]
	s_add_u32 s52, s52, 0x70000
	s_addc_u32 s53, s53, 0
	s_add_u32 s54, s54, 0x10000
	s_addc_u32 s55, s55, 0
; template <int TYPE>
; __device__ __forceinline__ void attn_item(const Ctx& a, int b, int h, int qt, LAS unsigned char* lds) {
;     ...
;             float mx = -1e30f;
; #pragma unroll
;             for (int kb = 0; kb < 2; ++kb)
; #pragma unroll
;                 for (int r = 0; r < 16; ++r) mx = fmaxf(mx, s[sub][kb][r]);
;             mx = fmaxf(mx, __shfl_xor(mx, 32));
;             const float delta = mrun - mref;
;             const bool bump = (mx - delta) > 8.f;
;             const bool rare = __builtin_amdgcn_ballot_w64(bump || delta != 0.f) != 0ull;
;             float fpost = 1.f;
;             if (rare) {
;                 const float mnew = bump ? mref + mx : mrun;
;                 const float pre = __builtin_amdgcn_exp2f(delta);
;                 fpost = __builtin_amdgcn_exp2f(mref - mnew);
;                 mrun = mnew;
;                 lrun *= pre;
; #pragma unroll
;                 for (int db = 0; db < 2; ++db)
; #pragma unroll
;                     for (int r = 0; r < 16; ++r) oacc[db][r] *= pre;
;             }
;             float ps = 0.f;
; #pragma unroll
;             for (int kb = 0; kb < 2; ++kb)
; #pragma unroll
;                 for (int r = 0; r < 16; ++r) { float p = __builtin_amdgcn_exp2f(s[sub][kb][r]); s[sub][kb][r] = p; ps += p; }
;             lrun += ps;
; #pragma unroll
;             for (int kb = 0; kb < 2; ++kb)
; #pragma unroll
;                 for (int c = 0; c < 2; ++c) {
;                     bf16x8 pb = pack8(s[sub][kb], c);
; #pragma unroll
;                     for (int db = 0; db < 2; ++db)
;                         oacc[db] = __builtin_amdgcn_mfma_f32_32x32x16_bf16(lds_a2(VT + (db * 32 + l32) * VLD + sub * 64 + kb * 32 + c * 16 + hb * 4), pb, oacc[db], 0, 0, 0);
;                 }
;             if (rare) {
;                 lrun *= fpost;
; #pragma unroll
;                 for (int db = 0; db < 2; ++db)
; #pragma unroll
;                     for (int r = 0; r < 16; ++r) oacc[db][r] *= fpost;
;             }
.Lat0_mid1:
	v_add_u32 v193, s8, v193
	v_add_u32 v200, s8, v200
	v_add_u32 v201, s8, v201
	s_barrier
	s_nop 7
	v_mfma_f32_32x32x16_bf16 v[16:31], v[146:149], v[48:51], v[16:31]
	ds_read_b64_tr_b16 v[170:171], v191 offset:6144
	ds_read_b64_tr_b16 v[172:173], v191 offset:7168
	v_max3_f32 v211, v211, v80, v81
	v_exp_f32 v80, v80
	v_exp_f32 v81, v81
	v_max3_f32 v211, v211, v82, v83
	v_exp_f32 v82, v82
	v_exp_f32 v83, v83
	v_add_f32 v188, v80, v81
	v_cvt_pk_bf16_f32 v80, v80, v81
	v_max3_f32 v211, v211, v84, v85
	v_exp_f32 v84, v84
	v_exp_f32 v85, v85
	v_add_f32 v188, v188, v82
	v_mfma_f32_32x32x16_bf16 v[32:47], v[150:153], v[48:51], v[32:47]
	ds_read_b64_tr_b16 v[174:175], v192 offset:6144
	ds_read_b64_tr_b16 v[176:177], v192 offset:7168
	v_add_f32 v188, v188, v83
	v_cvt_pk_bf16_f32 v81, v82, v83
	v_max3_f32 v211, v211, v86, v87
	v_exp_f32 v86, v86
	v_exp_f32 v87, v87
	v_add_f32 v188, v188, v84
	v_add_f32 v188, v188, v85
	v_cvt_pk_bf16_f32 v82, v84, v85
	v_max3_f32 v211, v211, v88, v89
	v_exp_f32 v88, v88
	v_exp_f32 v89, v89
	v_add_f32 v188, v188, v86
	v_mfma_f32_32x32x16_bf16 v[16:31], v[154:157], v[52:55], v[16:31]
	ds_read_b64_tr_b16 v[146:147], v191 offset:8192
	ds_read_b64_tr_b16 v[148:149], v191 offset:9216
	v_add_f32 v188, v188, v87
	v_cvt_pk_bf16_f32 v83, v86, v87
	v_max3_f32 v211, v211, v90, v91
	v_exp_f32 v90, v90
	v_exp_f32 v91, v91
	v_add_f32 v188, v188, v88
	v_add_f32 v188, v188, v89
	v_cvt_pk_bf16_f32 v84, v88, v89
	v_max3_f32 v211, v211, v92, v93
	v_exp_f32 v92, v92
	v_exp_f32 v93, v93
	v_add_f32 v188, v188, v90
	v_mfma_f32_32x32x16_bf16 v[32:47], v[158:161], v[52:55], v[32:47]
	ds_read_b64_tr_b16 v[150:151], v192 offset:8192
	ds_read_b64_tr_b16 v[152:153], v192 offset:9216
	v_add_f32 v188, v188, v91
	v_cvt_pk_bf16_f32 v85, v90, v91
	v_max3_f32 v211, v211, v94, v95
	v_exp_f32 v94, v94
	v_exp_f32 v95, v95
	v_add_f32 v188, v188, v92
	v_add_f32 v188, v188, v93
	v_cvt_pk_bf16_f32 v86, v92, v93
	v_add_f32 v188, v188, v94
	v_add_f32 v188, v188, v95
	v_cvt_pk_bf16_f32 v87, v94, v95
	v_max3_f32 v211, v211, v96, v97
	v_mfma_f32_32x32x16_bf16 v[16:31], v[162:165], v[64:67], v[16:31]
	ds_read_b64_tr_b16 v[154:155], v191 offset:10240
	ds_read_b64_tr_b16 v[156:157], v191 offset:11264
	v_exp_f32 v96, v96
	v_exp_f32 v97, v97
	v_max3_f32 v211, v211, v98, v99
	v_exp_f32 v98, v98
	v_exp_f32 v99, v99
	v_add_f32 v188, v188, v96
	v_add_f32 v188, v188, v97
	v_cvt_pk_bf16_f32 v96, v96, v97
	v_max3_f32 v211, v211, v100, v101
	v_exp_f32 v100, v100
	v_exp_f32 v101, v101
	v_add_f32 v188, v188, v98
	v_mfma_f32_32x32x16_bf16 v[32:47], v[166:169], v[64:67], v[32:47]
	ds_read_b64_tr_b16 v[158:159], v192 offset:10240
	ds_read_b64_tr_b16 v[160:161], v192 offset:11264
	v_add_f32 v188, v188, v99
	v_cvt_pk_bf16_f32 v97, v98, v99
	v_max3_f32 v211, v211, v102, v103
	v_exp_f32 v102, v102
	v_exp_f32 v103, v103
	v_add_f32 v188, v188, v100
	v_add_f32 v188, v188, v101
	v_cvt_pk_bf16_f32 v98, v100, v101
	v_max3_f32 v211, v211, v104, v105
	v_exp_f32 v104, v104
	v_exp_f32 v105, v105
	v_add_f32 v188, v188, v102
	s_waitcnt lgkmcnt(10)
	v_mfma_f32_32x32x16_bf16 v[16:31], v[170:173], v[68:71], v[16:31]
	ds_read_b64_tr_b16 v[162:163], v191 offset:12288
	ds_read_b64_tr_b16 v[164:165], v191 offset:13312
	v_add_f32 v188, v188, v103
	v_cvt_pk_bf16_f32 v99, v102, v103
	v_max3_f32 v211, v211, v106, v107
	v_exp_f32 v106, v106
	v_exp_f32 v107, v107
	v_add_f32 v188, v188, v104
	v_add_f32 v188, v188, v105
	v_cvt_pk_bf16_f32 v100, v104, v105
	v_max3_f32 v211, v211, v108, v109
	v_exp_f32 v108, v108
	v_exp_f32 v109, v109
	v_add_f32 v188, v188, v106
	s_waitcnt lgkmcnt(10)
	v_mfma_f32_32x32x16_bf16 v[32:47], v[174:177], v[68:71], v[32:47]
	ds_read_b64_tr_b16 v[166:167], v192 offset:12288
	ds_read_b64_tr_b16 v[168:169], v192 offset:13312
	v_add_f32 v188, v188, v107
	v_cvt_pk_bf16_f32 v101, v106, v107
	v_max3_f32 v211, v211, v110, v111
	v_exp_f32 v110, v110
	v_exp_f32 v111, v111
	v_add_f32 v188, v188, v108
	v_add_f32 v188, v188, v109
	v_cvt_pk_bf16_f32 v102, v108, v109
	v_add_f32 v188, v188, v110
	v_add_f32 v188, v188, v111
	v_cvt_pk_bf16_f32 v103, v110, v111
	v_add_f32 v206, v206, v188
	s_waitcnt lgkmcnt(10)
	v_mfma_f32_32x32x16_bf16 v[16:31], v[146:149], v[80:83], v[16:31]
	ds_read_b64_tr_b16 v[170:171], v191 offset:14336
	ds_read_b64_tr_b16 v[172:173], v191 offset:15360
	s_waitcnt lgkmcnt(10)
	v_mfma_f32_32x32x16_bf16 v[32:47], v[150:153], v[80:83], v[32:47]
	ds_read_b64_tr_b16 v[174:175], v192 offset:14336
	ds_read_b64_tr_b16 v[176:177], v192 offset:15360
	s_waitcnt lgkmcnt(10)
	v_mfma_f32_32x32x16_bf16 v[16:31], v[154:157], v[84:87], v[16:31]
	s_waitcnt lgkmcnt(8)
	v_mfma_f32_32x32x16_bf16 v[32:47], v[158:161], v[84:87], v[32:47]
	s_waitcnt lgkmcnt(6)
	v_mfma_f32_32x32x16_bf16 v[16:31], v[162:165], v[96:99], v[16:31]
	s_waitcnt lgkmcnt(4)
	v_mfma_f32_32x32x16_bf16 v[32:47], v[166:169], v[96:99], v[32:47]
	s_waitcnt lgkmcnt(2)
	v_mfma_f32_32x32x16_bf16 v[16:31], v[170:173], v[100:103], v[16:31]
	s_waitcnt lgkmcnt(0)
	v_mfma_f32_32x32x16_bf16 v[32:47], v[174:177], v[100:103], v[32:47]
	v_cmp_gt_f32_e64 s[40:41], v211, v207
	s_cmp_lg_u64 s[40:41], 0
	s_cbranch_scc0 .Lat0_pairend
	v_mov_b32 v1, v211
	s_nop 1
	v_permlane32_swap_b32 v1, v211
	v_max_f32 v1, v1, v211
	v_cmp_gt_f32 vcc, v1, v207
	s_nop 1
	v_cndmask_b32 v14, v205, v1, vcc
	v_sub_f32 v15, v205, v14
	v_exp_f32 v15, v15
	v_mov_b32 v205, v14
	v_add_f32 v207, 0x41000000, v14
	v_mul_f32 v16, v16, v15
	v_mul_f32 v17, v17, v15
	v_mul_f32 v18, v18, v15
	v_mul_f32 v19, v19, v15
	v_mul_f32 v20, v20, v15
	v_mul_f32 v21, v21, v15
	v_mul_f32 v22, v22, v15
	v_mul_f32 v23, v23, v15
	v_mul_f32 v24, v24, v15
	v_mul_f32 v25, v25, v15
	v_mul_f32 v26, v26, v15
	v_mul_f32 v27, v27, v15
	v_mul_f32 v28, v28, v15
	v_mul_f32 v29, v29, v15
	v_mul_f32 v30, v30, v15
	v_mul_f32 v31, v31, v15
	v_mul_f32 v32, v32, v15
	v_mul_f32 v33, v33, v15
	v_mul_f32 v34, v34, v15
	v_mul_f32 v35, v35, v15
	v_mul_f32 v36, v36, v15
	v_mul_f32 v37, v37, v15
	v_mul_f32 v38, v38, v15
	v_mul_f32 v39, v39, v15
	v_mul_f32 v40, v40, v15
	v_mul_f32 v41, v41, v15
	v_mul_f32 v42, v42, v15
	v_mul_f32 v43, v43, v15
	v_mul_f32 v44, v44, v15
	v_mul_f32 v45, v45, v15
	v_mul_f32 v46, v46, v15
	v_mul_f32 v47, v47, v15
	v_mul_f32 v206, v206, v15
	v_cmp_neq_f32_e64 s[36:37], 0, v205
	s_branch .Lat0_pairend

.Lat0_g0_end:
	s_waitcnt vmcnt(0)
	ds_write_b128 v193, v[2:5]
	ds_write_b128 v193, v[10:13] offset:13312
	ds_write_b128 v200, v[6:9]
	ds_write_b128 v200, v[136:139] offset:8192
	ds_write_b128 v201, v[140:143]
	s_cmp_eq_u32 s13, 2
	s_cselect_b32 s8, 0x1f800, 0
	s_sub_u32 s8, 0xa800, s8
	s_add_u32 s13, s13, 1
	s_cmp_eq_u32 s13, 3
	s_cselect_b32 s13, 0, s13
	s_waitcnt lgkmcnt(0)
	s_add_u32 s9, s26, 2
	s_cmp_lt_u32 s9, s30
	s_cbranch_scc0 .Lat0_mid2
	global_load_dwordx4 v[2:5], v184, s[52:53]
	global_load_dwordx4 v[6:9], v184, s[52:53] offset:128
	global_load_dwordx4 v[10:13], v185, s[52:53]
	global_load_dwordx4 v[136:139], v185, s[52:53] offset:128
	global_load_dwordx4 v[140:143], v186, s[54:55]
	s_add_u32 s52, s52, 0x70000
	s_addc_u32 s53, s53, 0
	s_add_u32 s54, s54, 0x10000
	s_addc_u32 s55, s55, 0
.Lat0_mid2:
	v_add_u32 v193, s8, v193
	v_add_u32 v200, s8, v200
	v_add_u32 v201, s8, v201
	s_barrier

; #define LAS __attribute__((address_space(3)))
; template <int TYPE>
; __device__ __forceinline__ void attn_item(const Ctx& a, int b, int h, int qt, LAS unsigned char* lds) {
;     ...
;     for (int kp = 0; kp < npair; ++kp) {
;         const int bufi = kp & 1;
;         if (kp + 1 < npair) AT_LOAD(kp + 1);
;         LAS unsigned char* Bf = lds + bufi * BUF;
;     ...
;         if (kp + 1 < npair) AT_STORE(bufi ^ 1);
;         __syncthreads();
;     }
.Lat0_g1_end:
.Lat0_pairend:
	s_cmp_eq_u32 s12, 2
	s_cselect_b32 s8, 0x1f800, 0
	s_sub_u32 s8, 0xa800, s8
	v_add_u32 v190, s8, v190
	v_add_u32 v191, s8, v191
	v_add_u32 v192, s8, v192
	s_add_u32 s12, s12, 1
	s_cmp_eq_u32 s12, 3
	s_cselect_b32 s12, 0, s12
	s_add_u32 s26, s26, 1
	s_waitcnt lgkmcnt(0)
	s_cmp_lt_u32 s26, s30
	s_cbranch_scc1 .Lat0_loop

; #define LAS __attribute__((address_space(3)))
; template <int TYPE>
; __device__ __forceinline__ void attn_item(const Ctx& a, int b, int h, int qt, LAS unsigned char* lds) {
;     ...
;     const int qrow = qt * 256 + wv * 32 + l32;
;     bf16x8 Q[NKK];
;     {
;         const bf16_t* qp = TYPE == 0 ? mr + (size_t)qrow * MR + h * 96 : pa + (size_t)qrow * PA + C_MQ + h * 64;
; #pragma unroll
;         for (int kk = 0; kk < NKK; ++kk) Q[kk] = *(const bf16x8*)(qp + kk * 16 + hb * 8);
;     }
;     unsigned qmask = 0xffffffffu;
;     if (TYPE == 1) qmask = ((const unsigned*)(a.ws + WS_MASK))[(size_t)h * SEQ + qrow];
;     f32x16 oacc[2];
; #pragma unroll
;     for (int db = 0; db < 2; ++db)
; #pragma unroll
;         for (int r = 0; r < 16; ++r) oacc[db][r] = 0.f;
;     float mrun = 0.f, lrun = 0.f;
;     const int npair = (qt + 1) * 2;
;     u32x4 kreg[NKC], vreg[2];
;     ...
;     AT_LOAD(0); AT_STORE(0);
;     __syncthreads();
;     for (int kp = 0; kp < npair; ++kp) {
;         const int bufi = kp & 1;
;         if (kp + 1 < npair) AT_LOAD(kp + 1);
;         LAS unsigned char* Bf = lds + bufi * BUF;
;         const LAS bf16_t* Kt = (const LAS bf16_t*)Bf; const LAS bf16_t* VT = (const LAS bf16_t*)(Bf + KBYTES);
;         f32x16 s[2][2];
;         bool act[2];
;         const float mref = mrun;
; #pragma unroll
;         for (int sub = 0; sub < 2; ++sub) {
;             const int kloc = kp * 2 + sub - qt * 4;
;             act[sub] = (kloc < 0) || (kloc * 64 <= wv * 32 + 31);
;             if (TYPE == 1 && kloc < 0) act[sub] = __builtin_amdgcn_ballot_w64((qmask >> ((kp * 2 + sub) >> 2)) & 1u) != 0ull;
; #pragma unroll
;             for (int kb = 0; kb < 2; ++kb)
; #pragma unroll
;                 for (int r = 0; r < 16; ++r) s[sub][kb][r] = -mref;
.Lat1_entry:
	s_lshr_b32 s47, s12, 4
	s_sub_u32 s47, 31, s47
	s_and_b32 s50, s12, 7
	v_lshrrev_b32 v1, 6, v179
	s_add_u32 s30, s47, 1
	s_lshl_b32 s30, s30, 1
	v_readfirstlane_b32 s51, v1
	v_and_b32 v14, 31, v195
	v_lshrrev_b32 v15, 5, v195
	s_lshl_b32 s8, s47, 8
	s_lshl_b32 s9, s51, 5
	s_add_u32 s8, s8, s9
	v_add_u32 v144, s8, v14
	v_add_u32 v208, s9, v14
	v_lshlrev_b32 v181, 2, v15
	v_sub_u32 v208, v208, v181
	s_lshl_b32 s9, s50, 7
	s_add_u32 s56, s70, 0x1350
	s_addc_u32 s57, s71, 0
	s_add_u32 s56, s56, s9
	s_addc_u32 s57, s57, 0
	v_lshlrev_b32 v181, 13, v144
	v_lshl_add_u32 v181, v15, 4, v181
	global_load_dwordx4 v[112:115], v181, s[56:57] offset:0
	global_load_dwordx4 v[116:119], v181, s[56:57] offset:32
	global_load_dwordx4 v[120:123], v181, s[56:57] offset:64
	global_load_dwordx4 v[124:127], v181, s[56:57] offset:96
	s_lshl_b32 s9, s50, 15
	s_add_u32 s56, s16, 0x58b0000
	s_addc_u32 s57, s17, 0
	s_add_u32 s56, s56, s9
	s_addc_u32 s57, s57, 0
	v_lshlrev_b32 v212, 2, v144
	global_load_dword v209, v212, s[56:57]
	v_lshrrev_b32 v181, 3, v179
	v_and_b32 v212, 7, v179
	s_lshl_b32 s9, s50, 7
	s_add_u32 s52, s70, 0x1750
	s_addc_u32 s53, s71, 0
	s_add_u32 s52, s52, s9
	s_addc_u32 s53, s53, 0
	v_lshlrev_b32 v184, 13, v181
	v_lshl_add_u32 v184, v212, 4, v184
	v_add_u32 v185, 0x80000, v184
	v_mul_u32_u24 v190, 144, v14
	v_lshl_add_u32 v190, v15, 4, v190
	v_mul_u32_u24 v193, 144, v181
	v_lshl_add_u32 v193, v212, 4, v193
	v_and_b32 v1, 2, v181
	v_lshlrev_b32 v1, 5, v1
	v_lshlrev_b32 v188, 4, v212
	v_xor_b32 v1, v1, v188
	v_lshl_add_u32 v200, v181, 7, v1
	v_add_u32 v200, 18432, v200
	v_bfe_u32 v1, v195, 2, 2
	v_lshlrev_b32 v191, 7, v1
	v_bfe_u32 v1, v195, 3, 1
	v_lshl_add_u32 v191, v1, 6, v191
	v_bfe_u32 v1, v195, 4, 1
	v_lshl_add_u32 v191, v1, 5, v191
	v_and_b32 v1, 3, v195
	v_lshl_add_u32 v191, v1, 3, v191
	v_lshl_add_u32 v191, v15, 9, v191
	v_add_u32 v191, 18432, v191
	v_xor_b32 v192, 64, v191
	global_load_dwordx4 v[2:5], v184, s[52:53]
	global_load_dwordx4 v[6:9], v184, s[52:53] offset:1024
	global_load_dwordx4 v[10:13], v185, s[52:53]
	global_load_dwordx4 v[136:139], v185, s[52:53] offset:1024
	s_add_u32 s52, s52, 0x100000
	s_addc_u32 s53, s53, 0
	v_mov_b32 v16, 0
	v_mov_b32 v17, 0
	v_mov_b32 v18, 0
	v_mov_b32 v19, 0
	v_mov_b32 v20, 0
	v_mov_b32 v21, 0
	v_mov_b32 v22, 0
	v_mov_b32 v23, 0
	v_mov_b32 v24, 0
	v_mov_b32 v25, 0
	v_mov_b32 v26, 0
	v_mov_b32 v27, 0
	v_mov_b32 v28, 0
	v_mov_b32 v29, 0
	v_mov_b32 v30, 0
	v_mov_b32 v31, 0
	v_mov_b32 v32, 0
	v_mov_b32 v33, 0
	v_mov_b32 v34, 0
	v_mov_b32 v35, 0
	v_mov_b32 v36, 0
	v_mov_b32 v37, 0
	v_mov_b32 v38, 0
	v_mov_b32 v39, 0
	v_mov_b32 v40, 0
	v_mov_b32 v41, 0
	v_mov_b32 v42, 0
	v_mov_b32 v43, 0
	v_mov_b32 v44, 0
	v_mov_b32 v45, 0
	v_mov_b32 v46, 0
	v_mov_b32 v47, 0
	v_mov_b32 v205, 0
	v_mov_b32 v206, 0
	v_mov_b32 v207, 0x41000000
	s_mov_b64 s[36:37], 0
	s_mov_b32 s26, 0
	s_waitcnt vmcnt(0)
	ds_write_b128 v193, v[2:5]
	ds_write_b128 v193, v[10:13] offset:9216
	ds_write_b128 v200, v[6:9]
	ds_write_b128 v200, v[136:139] offset:8192
	s_waitcnt lgkmcnt(0)
	global_load_dwordx4 v[2:5], v184, s[52:53]
	global_load_dwordx4 v[6:9], v184, s[52:53] offset:1024
	global_load_dwordx4 v[10:13], v185, s[52:53]
	global_load_dwordx4 v[136:139], v185, s[52:53] offset:1024
	s_add_u32 s52, s52, 0x100000
	s_addc_u32 s53, s53, 0
	s_mov_b32 s8, 0x8800
	v_add_u32 v193, s8, v193
	v_add_u32 v200, s8, v200
	s_mov_b32 s12, 0
	s_mov_b32 s13, 1
	s_waitcnt lgkmcnt(0)
	s_barrier
.Lat1_loop:
	s_add_u32 s8, s26, 2
	s_cmp_ge_u32 s8, s30
	s_cselect_b32 s57, 1, 0
	s_lshr_b32 s8, s26, 1
	v_lshrrev_b32 v1, s8, v209
	v_and_b32 v1, 1, v1
	v_sub_u32 v210, 0, v1
	v_cmp_ne_u32_e64 s[38:39], 0, v1
	s_cmp_eq_u32 s57, 1
	s_cbranch_scc1 .Lat1_gen
	s_cmp_eq_u64 s[38:39], 0
	s_cbranch_scc1 .Lat1_skip
	s_cmp_lg_u64 s[36:37], 0
	s_cbranch_scc1 .Lat1_gen
	v_mov_b32 v211, v0
	ds_read_b128 v[146:149], v190 offset:0
	ds_read_b128 v[150:153], v190 offset:4608
	ds_read_b128 v[154:157], v190 offset:32
	ds_read_b128 v[158:161], v190 offset:4640
	ds_read_b128 v[162:165], v190 offset:64
	ds_read_b128 v[166:169], v190 offset:4672
	s_waitcnt lgkmcnt(5)
	v_mfma_f32_32x32x16_bf16 v[48:63], v[146:149], v[112:115], 0
	ds_read_b128 v[170:173], v190 offset:96
	s_waitcnt lgkmcnt(5)
	v_mfma_f32_32x32x16_bf16 v[64:79], v[150:153], v[112:115], 0
	ds_read_b128 v[174:177], v190 offset:4704
	s_waitcnt lgkmcnt(5)
	v_mfma_f32_32x32x16_bf16 v[48:63], v[154:157], v[116:119], v[48:63]
	ds_read_b128 v[146:149], v190 offset:9216
	s_waitcnt lgkmcnt(5)
	v_mfma_f32_32x32x16_bf16 v[64:79], v[158:161], v[116:119], v[64:79]
	ds_read_b128 v[150:153], v190 offset:13824
	s_waitcnt lgkmcnt(5)
	v_mfma_f32_32x32x16_bf16 v[48:63], v[162:165], v[120:123], v[48:63]
	ds_read_b128 v[154:157], v190 offset:9248
	s_waitcnt lgkmcnt(5)
	v_mfma_f32_32x32x16_bf16 v[64:79], v[166:169], v[120:123], v[64:79]
	ds_read_b128 v[158:161], v190 offset:13856
	s_waitcnt lgkmcnt(5)
	v_mfma_f32_32x32x16_bf16 v[48:63], v[170:173], v[124:127], v[48:63]
	ds_read_b128 v[162:165], v190 offset:9280
	s_waitcnt lgkmcnt(5)
	v_mfma_f32_32x32x16_bf16 v[64:79], v[174:177], v[124:127], v[64:79]
	ds_read_b128 v[166:169], v190 offset:13888
	s_waitcnt lgkmcnt(5)
	v_mfma_f32_32x32x16_bf16 v[80:95], v[146:149], v[112:115], 0
	ds_read_b128 v[170:173], v190 offset:9312
	s_nop 4
	v_max3_f32 v211, v211, v48, v49
	v_exp_f32 v48, v48
	v_exp_f32 v49, v49
	v_max3_f32 v211, v211, v50, v51
	v_exp_f32 v50, v50
	v_exp_f32 v51, v51
	v_add_f32 v188, v48, v49
	v_cvt_pk_bf16_f32 v48, v48, v49
	v_and_b32 v48, v48, v210
	v_max3_f32 v211, v211, v52, v53
	v_exp_f32 v52, v52
	v_exp_f32 v53, v53
	v_add_f32 v188, v188, v50
	v_add_f32 v188, v188, v51
	s_waitcnt lgkmcnt(5)
; template <int TYPE>
; __device__ __forceinline__ void attn_item(const Ctx& a, int b, int h, int qt, LAS unsigned char* lds) {
;     ...
;         for (int kk = 0; kk < NKK; ++kk)
; #pragma unroll
;             for (int sub = 0; sub < 2; ++sub)
;                 if (act[sub]) {
; #pragma unroll
;                     for (int kb = 0; kb < 2; ++kb) {
;                         bf16x8 ka = *(const LAS bf16x8*)(Kt + (sub * 64 + kb * 32 + l32) * KLD + kk * 16 + hb * 8);
;                         s[sub][kb] = __builtin_amdgcn_mfma_f32_32x32x16_bf16(ka, Q[kk], s[sub][kb], 0, 0, 0);
;                     }
;                 }
; #pragma unroll
;         for (int sub = 0; sub < 2; ++sub) {
;             if (!act[sub]) continue;
;             const int kt = kp * 2 + sub, kloc = kt - qt * 4;
;             if (kloc >= 0) {
; #pragma unroll
;                 for (int kb = 0; kb < 2; ++kb)
; #pragma unroll
;                     for (int r = 0; r < 16; ++r) { int kabs = kt * 64 + kb * 32 + (r >> 2) * 8 + hb * 4 + (r & 3); if (kabs > qrow) s[sub][kb][r] = -1e30f; }
;             } else if (TYPE == 1) {
;                 if (!((qmask >> (kt >> 2)) & 1u)) {
; #pragma unroll
;                     for (int kb = 0; kb < 2; ++kb)
; #pragma unroll
;                         for (int r = 0; r < 16; ++r) s[sub][kb][r] = -1e30f;
;                 }
;             }
;             float mx = -1e30f;
; #pragma unroll
;             for (int kb = 0; kb < 2; ++kb)
; #pragma unroll
;                 for (int r = 0; r < 16; ++r) mx = fmaxf(mx, s[sub][kb][r]);
;             mx = fmaxf(mx, __shfl_xor(mx, 32));
;             const float delta = mrun - mref;
;             const bool bump = (mx - delta) > 8.f;
;             const bool rare = __builtin_amdgcn_ballot_w64(bump || delta != 0.f) != 0ull;
;             float fpost = 1.f;
;             if (rare) {
;                 const float mnew = bump ? mref + mx : mrun;
;                 const float pre = __builtin_amdgcn_exp2f(delta);
;                 fpost = __builtin_amdgcn_exp2f(mref - mnew);
;                 mrun = mnew;
;                 lrun *= pre;
; #pragma unroll
;                 for (int db = 0; db < 2; ++db)
; #pragma unroll
;                     for (int r = 0; r < 16; ++r) oacc[db][r] *= pre;
;             }
;             float ps = 0.f;
; #pragma unroll
;             for (int kb = 0; kb < 2; ++kb)
; #pragma unroll
	v_mfma_f32_32x32x16_bf16 v[96:111], v[150:153], v[112:115], 0
	ds_read_b128 v[174:177], v190 offset:13920
	v_cvt_pk_bf16_f32 v49, v50, v51
	v_and_b32 v49, v49, v210
	v_max3_f32 v211, v211, v54, v55
	v_exp_f32 v54, v54
	v_exp_f32 v55, v55
	v_add_f32 v188, v188, v52
	v_add_f32 v188, v188, v53
	v_cvt_pk_bf16_f32 v50, v52, v53
	v_and_b32 v50, v50, v210
	v_max3_f32 v211, v211, v56, v57
	v_exp_f32 v56, v56
	v_exp_f32 v57, v57
	v_add_f32 v188, v188, v54
	v_add_f32 v188, v188, v55
	s_waitcnt lgkmcnt(5)
	v_mfma_f32_32x32x16_bf16 v[80:95], v[154:157], v[116:119], v[80:95]
	ds_read_b64_tr_b16 v[146:147], v191 offset:0
	ds_read_b64_tr_b16 v[148:149], v191 offset:1024
	v_cvt_pk_bf16_f32 v51, v54, v55
	v_and_b32 v51, v51, v210
	v_max3_f32 v211, v211, v58, v59
	v_exp_f32 v58, v58
	v_exp_f32 v59, v59
	v_add_f32 v188, v188, v56
	v_add_f32 v188, v188, v57
	v_cvt_pk_bf16_f32 v52, v56, v57
	v_and_b32 v52, v52, v210
	v_max3_f32 v211, v211, v60, v61
	v_exp_f32 v60, v60
	v_exp_f32 v61, v61
	v_add_f32 v188, v188, v58
	v_add_f32 v188, v188, v59
	s_waitcnt lgkmcnt(6)
	v_mfma_f32_32x32x16_bf16 v[96:111], v[158:161], v[116:119], v[96:111]
	ds_read_b64_tr_b16 v[150:151], v192 offset:0
	ds_read_b64_tr_b16 v[152:153], v192 offset:1024
	v_cvt_pk_bf16_f32 v53, v58, v59
	v_and_b32 v53, v53, v210
	v_max3_f32 v211, v211, v62, v63
	v_exp_f32 v62, v62
	v_exp_f32 v63, v63
	v_add_f32 v188, v188, v60
	v_add_f32 v188, v188, v61
	v_cvt_pk_bf16_f32 v54, v60, v61
	v_and_b32 v54, v54, v210
	v_add_f32 v188, v188, v62
	v_add_f32 v188, v188, v63
	v_cvt_pk_bf16_f32 v55, v62, v63
	v_and_b32 v55, v55, v210
	v_max3_f32 v211, v211, v64, v65
	s_waitcnt lgkmcnt(7)
	v_mfma_f32_32x32x16_bf16 v[80:95], v[162:165], v[120:123], v[80:95]
	ds_read_b64_tr_b16 v[154:155], v191 offset:2048
	ds_read_b64_tr_b16 v[156:157], v191 offset:3072
	v_exp_f32 v64, v64
	v_exp_f32 v65, v65
	v_max3_f32 v211, v211, v66, v67
	v_exp_f32 v66, v66
	v_exp_f32 v67, v67
	v_add_f32 v188, v188, v64
	v_add_f32 v188, v188, v65
	v_cvt_pk_bf16_f32 v64, v64, v65
	v_and_b32 v64, v64, v210
	v_max3_f32 v211, v211, v68, v69
	v_exp_f32 v68, v68
	v_exp_f32 v69, v69
	v_add_f32 v188, v188, v66
	v_add_f32 v188, v188, v67
	s_waitcnt lgkmcnt(8)
	v_mfma_f32_32x32x16_bf16 v[96:111], v[166:169], v[120:123], v[96:111]
	ds_read_b64_tr_b16 v[158:159], v192 offset:2048
	ds_read_b64_tr_b16 v[160:161], v192 offset:3072
	v_cvt_pk_bf16_f32 v65, v66, v67
	v_and_b32 v65, v65, v210
	v_max3_f32 v211, v211, v70, v71
	v_exp_f32 v70, v70
	v_exp_f32 v71, v71
	v_add_f32 v188, v188, v68
	v_add_f32 v188, v188, v69
	v_cvt_pk_bf16_f32 v66, v68, v69
	v_and_b32 v66, v66, v210
	v_max3_f32 v211, v211, v72, v73
	v_exp_f32 v72, v72
	v_exp_f32 v73, v73
	v_add_f32 v188, v188, v70
	v_add_f32 v188, v188, v71
	s_waitcnt lgkmcnt(9)
	v_mfma_f32_32x32x16_bf16 v[80:95], v[170:173], v[124:127], v[80:95]
	ds_read_b64_tr_b16 v[162:163], v191 offset:4096
	ds_read_b64_tr_b16 v[164:165], v191 offset:5120
	v_cvt_pk_bf16_f32 v67, v70, v71
	v_and_b32 v67, v67, v210
	v_max3_f32 v211, v211, v74, v75
	v_exp_f32 v74, v74
	v_exp_f32 v75, v75
	v_add_f32 v188, v188, v72
	v_add_f32 v188, v188, v73
	v_cvt_pk_bf16_f32 v68, v72, v73
	v_and_b32 v68, v68, v210
	v_max3_f32 v211, v211, v76, v77
	v_exp_f32 v76, v76
	v_exp_f32 v77, v77
	v_add_f32 v188, v188, v74
	v_add_f32 v188, v188, v75
	s_waitcnt lgkmcnt(10)
	v_mfma_f32_32x32x16_bf16 v[96:111], v[174:177], v[124:127], v[96:111]
	ds_read_b64_tr_b16 v[166:167], v192 offset:4096
	ds_read_b64_tr_b16 v[168:169], v192 offset:5120
	v_cvt_pk_bf16_f32 v69, v74, v75
	v_and_b32 v69, v69, v210
	v_max3_f32 v211, v211, v78, v79
	v_exp_f32 v78, v78
	v_exp_f32 v79, v79
	v_add_f32 v188, v188, v76
	v_add_f32 v188, v188, v77
	v_cvt_pk_bf16_f32 v70, v76, v77
	v_and_b32 v70, v70, v210
	v_add_f32 v188, v188, v78
	v_add_f32 v188, v188, v79
	v_cvt_pk_bf16_f32 v71, v78, v79
	v_and_b32 v71, v71, v210
	v_and_b32 v188, v188, v210
	v_add_f32 v206, v206, v188
	s_waitcnt vmcnt(0)
	ds_write_b128 v193, v[2:5]
	ds_write_b128 v193, v[10:13] offset:9216
	ds_write_b128 v200, v[6:9]
	ds_write_b128 v200, v[136:139] offset:8192
	s_cmp_eq_u32 s13, 2
	s_cselect_b32 s8, 0x19800, 0
	s_sub_u32 s8, 0x8800, s8
	s_add_u32 s13, s13, 1
	s_cmp_eq_u32 s13, 3
	s_cselect_b32 s13, 0, s13
	s_waitcnt lgkmcnt(0)
	s_add_u32 s9, s26, 2
	s_cmp_lt_u32 s9, s30
	s_cbranch_scc0 .Lat1_mid3
	global_load_dwordx4 v[2:5], v184, s[52:53]
	global_load_dwordx4 v[6:9], v184, s[52:53] offset:1024
	global_load_dwordx4 v[10:13], v185, s[52:53]
	global_load_dwordx4 v[136:139], v185, s[52:53] offset:1024
	s_add_u32 s52, s52, 0x100000
	s_addc_u32 s53, s53, 0
; template <int TYPE>
; __device__ __forceinline__ void attn_item(const Ctx& a, int b, int h, int qt, LAS unsigned char* lds) {
;     ...
;             } else if (TYPE == 1) {
;                 if (!((qmask >> (kt >> 2)) & 1u)) {
; #pragma unroll
;                     for (int kb = 0; kb < 2; ++kb)
; #pragma unroll
;                         for (int r = 0; r < 16; ++r) s[sub][kb][r] = -1e30f;
;                 }
;             }
;             float mx = -1e30f;
; #pragma unroll
;             for (int kb = 0; kb < 2; ++kb)
; #pragma unroll
;                 for (int r = 0; r < 16; ++r) mx = fmaxf(mx, s[sub][kb][r]);
;             mx = fmaxf(mx, __shfl_xor(mx, 32));
;             const float delta = mrun - mref;
;             const bool bump = (mx - delta) > 8.f;
;             const bool rare = __builtin_amdgcn_ballot_w64(bump || delta != 0.f) != 0ull;
;             float fpost = 1.f;
;             if (rare) {
;                 const float mnew = bump ? mref + mx : mrun;
;                 const float pre = __builtin_amdgcn_exp2f(delta);
;                 fpost = __builtin_amdgcn_exp2f(mref - mnew);
;                 mrun = mnew;
;                 lrun *= pre;
; #pragma unroll
;                 for (int db = 0; db < 2; ++db)
; #pragma unroll
;                     for (int r = 0; r < 16; ++r) oacc[db][r] *= pre;
;             }
;             float ps = 0.f;
; #pragma unroll
;             for (int kb = 0; kb < 2; ++kb)
; #pragma unroll
;                 for (int r = 0; r < 16; ++r) { float p = __builtin_amdgcn_exp2f(s[sub][kb][r]); s[sub][kb][r] = p; ps += p; }
;             lrun += ps;
; #pragma unroll
;             for (int kb = 0; kb < 2; ++kb)
; #pragma unroll
;                 for (int c = 0; c < 2; ++c) {
;                     bf16x8 pb = pack8(s[sub][kb], c);
; #pragma unroll
;                     for (int db = 0; db < 2; ++db)
;                         oacc[db] = __builtin_amdgcn_mfma_f32_32x32x16_bf16(lds_a2(VT + (db * 32 + l32) * VLD + sub * 64 + kb * 32 + c * 16 + hb * 4), pb, oacc[db], 0, 0, 0);
;                 }
;             if (rare) {
;                 lrun *= fpost;
; #pragma unroll
;                 for (int db = 0; db < 2; ++db)
; #pragma unroll
;                     for (int r = 0; r < 16; ++r) oacc[db][r] *= fpost;
;             }
.Lat1_mid3:
	v_add_u32 v193, s8, v193
	v_add_u32 v200, s8, v200
	s_barrier
	s_nop 7
	s_nop 0
	v_mfma_f32_32x32x16_bf16 v[16:31], v[146:149], v[48:51], v[16:31]
	ds_read_b64_tr_b16 v[170:171], v191 offset:6144
	ds_read_b64_tr_b16 v[172:173], v191 offset:7168
	v_max3_f32 v211, v211, v80, v81
	v_exp_f32 v80, v80
	v_exp_f32 v81, v81
	v_max3_f32 v211, v211, v82, v83
	v_exp_f32 v82, v82
	v_exp_f32 v83, v83
	v_add_f32 v188, v80, v81
	v_cvt_pk_bf16_f32 v80, v80, v81
	v_and_b32 v80, v80, v210
	v_max3_f32 v211, v211, v84, v85
	v_exp_f32 v84, v84
	v_exp_f32 v85, v85
	v_add_f32 v188, v188, v82
	v_add_f32 v188, v188, v83
	v_mfma_f32_32x32x16_bf16 v[32:47], v[150:153], v[48:51], v[32:47]
	ds_read_b64_tr_b16 v[174:175], v192 offset:6144
	ds_read_b64_tr_b16 v[176:177], v192 offset:7168
	v_cvt_pk_bf16_f32 v81, v82, v83
	v_and_b32 v81, v81, v210
	v_max3_f32 v211, v211, v86, v87
	v_exp_f32 v86, v86
	v_exp_f32 v87, v87
	v_add_f32 v188, v188, v84
	v_add_f32 v188, v188, v85
	v_cvt_pk_bf16_f32 v82, v84, v85
	v_and_b32 v82, v82, v210
	v_max3_f32 v211, v211, v88, v89
	v_exp_f32 v88, v88
	v_exp_f32 v89, v89
	v_add_f32 v188, v188, v86
	v_add_f32 v188, v188, v87
	v_mfma_f32_32x32x16_bf16 v[16:31], v[154:157], v[52:55], v[16:31]
	ds_read_b64_tr_b16 v[146:147], v191 offset:8192
	ds_read_b64_tr_b16 v[148:149], v191 offset:9216
	v_cvt_pk_bf16_f32 v83, v86, v87
	v_and_b32 v83, v83, v210
	v_max3_f32 v211, v211, v90, v91
	v_exp_f32 v90, v90
	v_exp_f32 v91, v91
	v_add_f32 v188, v188, v88
	v_add_f32 v188, v188, v89
	v_cvt_pk_bf16_f32 v84, v88, v89
	v_and_b32 v84, v84, v210
	v_max3_f32 v211, v211, v92, v93
	v_exp_f32 v92, v92
	v_exp_f32 v93, v93
	v_add_f32 v188, v188, v90
	v_add_f32 v188, v188, v91
	v_mfma_f32_32x32x16_bf16 v[32:47], v[158:161], v[52:55], v[32:47]
	ds_read_b64_tr_b16 v[150:151], v192 offset:8192
	ds_read_b64_tr_b16 v[152:153], v192 offset:9216
	v_cvt_pk_bf16_f32 v85, v90, v91
	v_and_b32 v85, v85, v210
	v_max3_f32 v211, v211, v94, v95
	v_exp_f32 v94, v94
	v_exp_f32 v95, v95
	v_add_f32 v188, v188, v92
	v_add_f32 v188, v188, v93
	v_cvt_pk_bf16_f32 v86, v92, v93
	v_and_b32 v86, v86, v210
	v_add_f32 v188, v188, v94
	v_add_f32 v188, v188, v95
	v_cvt_pk_bf16_f32 v87, v94, v95
	v_and_b32 v87, v87, v210
	v_max3_f32 v211, v211, v96, v97
	v_mfma_f32_32x32x16_bf16 v[16:31], v[162:165], v[64:67], v[16:31]
	ds_read_b64_tr_b16 v[154:155], v191 offset:10240
	ds_read_b64_tr_b16 v[156:157], v191 offset:11264
	v_exp_f32 v96, v96
	v_exp_f32 v97, v97
	v_max3_f32 v211, v211, v98, v99
	v_exp_f32 v98, v98
	v_exp_f32 v99, v99
	v_add_f32 v188, v188, v96
	v_add_f32 v188, v188, v97
	v_cvt_pk_bf16_f32 v96, v96, v97
	v_and_b32 v96, v96, v210
	v_max3_f32 v211, v211, v100, v101
	v_exp_f32 v100, v100
	v_exp_f32 v101, v101
	v_add_f32 v188, v188, v98
	v_add_f32 v188, v188, v99
	v_mfma_f32_32x32x16_bf16 v[32:47], v[166:169], v[64:67], v[32:47]
	ds_read_b64_tr_b16 v[158:159], v192 offset:10240
	ds_read_b64_tr_b16 v[160:161], v192 offset:11264
	v_cvt_pk_bf16_f32 v97, v98, v99
	v_and_b32 v97, v97, v210
	v_max3_f32 v211, v211, v102, v103
	v_exp_f32 v102, v102
	v_exp_f32 v103, v103
	v_add_f32 v188, v188, v100
	v_add_f32 v188, v188, v101
	v_cvt_pk_bf16_f32 v98, v100, v101
	v_and_b32 v98, v98, v210
	v_max3_f32 v211, v211, v104, v105
	v_exp_f32 v104, v104
	v_exp_f32 v105, v105
	v_add_f32 v188, v188, v102
	v_add_f32 v188, v188, v103
	s_waitcnt lgkmcnt(10)
	v_mfma_f32_32x32x16_bf16 v[16:31], v[170:173], v[68:71], v[16:31]
	ds_read_b64_tr_b16 v[162:163], v191 offset:12288
	ds_read_b64_tr_b16 v[164:165], v191 offset:13312
	v_cvt_pk_bf16_f32 v99, v102, v103
	v_and_b32 v99, v99, v210
	v_max3_f32 v211, v211, v106, v107
	v_exp_f32 v106, v106
	v_exp_f32 v107, v107
	v_add_f32 v188, v188, v104
	v_add_f32 v188, v188, v105
	v_cvt_pk_bf16_f32 v100, v104, v105
	v_and_b32 v100, v100, v210
	v_max3_f32 v211, v211, v108, v109
	v_exp_f32 v108, v108
	v_exp_f32 v109, v109
	v_add_f32 v188, v188, v106
	v_add_f32 v188, v188, v107
	s_waitcnt lgkmcnt(10)
	v_mfma_f32_32x32x16_bf16 v[32:47], v[174:177], v[68:71], v[32:47]
	ds_read_b64_tr_b16 v[166:167], v192 offset:12288
	ds_read_b64_tr_b16 v[168:169], v192 offset:13312
	v_cvt_pk_bf16_f32 v101, v106, v107
	v_and_b32 v101, v101, v210
	v_max3_f32 v211, v211, v110, v111
	v_exp_f32 v110, v110
	v_exp_f32 v111, v111
	v_add_f32 v188, v188, v108
	v_add_f32 v188, v188, v109
	v_cvt_pk_bf16_f32 v102, v108, v109
	v_and_b32 v102, v102, v210
	v_add_f32 v188, v188, v110
	v_add_f32 v188, v188, v111
	v_cvt_pk_bf16_f32 v103, v110, v111
	v_and_b32 v103, v103, v210
	v_and_b32 v188, v188, v210
	v_add_f32 v206, v206, v188
	s_waitcnt lgkmcnt(10)
	v_mfma_f32_32x32x16_bf16 v[16:31], v[146:149], v[80:83], v[16:31]
	ds_read_b64_tr_b16 v[170:171], v191 offset:14336
	ds_read_b64_tr_b16 v[172:173], v191 offset:15360
	s_waitcnt lgkmcnt(10)
	v_mfma_f32_32x32x16_bf16 v[32:47], v[150:153], v[80:83], v[32:47]
	ds_read_b64_tr_b16 v[174:175], v192 offset:14336
	ds_read_b64_tr_b16 v[176:177], v192 offset:15360
	s_waitcnt lgkmcnt(10)
	v_mfma_f32_32x32x16_bf16 v[16:31], v[154:157], v[84:87], v[16:31]
	s_waitcnt lgkmcnt(8)
	v_mfma_f32_32x32x16_bf16 v[32:47], v[158:161], v[84:87], v[32:47]
	s_waitcnt lgkmcnt(6)
	v_mfma_f32_32x32x16_bf16 v[16:31], v[162:165], v[96:99], v[16:31]
	s_waitcnt lgkmcnt(4)
	v_mfma_f32_32x32x16_bf16 v[32:47], v[166:169], v[96:99], v[32:47]
	s_waitcnt lgkmcnt(2)
	v_mfma_f32_32x32x16_bf16 v[16:31], v[170:173], v[100:103], v[16:31]
	s_waitcnt lgkmcnt(0)
	v_mfma_f32_32x32x16_bf16 v[32:47], v[174:177], v[100:103], v[32:47]
	v_cndmask_b32_e64 v211, v0, v211, s[38:39]
	v_cmp_gt_f32_e64 s[40:41], v211, v207
	s_cmp_lg_u64 s[40:41], 0
	s_cbranch_scc0 .Lat1_pairend
	v_mov_b32 v1, v211
	s_nop 1
	v_permlane32_swap_b32 v1, v211
	v_max_f32 v1, v1, v211
	v_cmp_gt_f32 vcc, v1, v207
	s_nop 1
	v_cndmask_b32 v14, v205, v1, vcc
	v_sub_f32 v15, v205, v14
	v_exp_f32 v15, v15
	v_mov_b32 v205, v14
	v_add_f32 v207, 0x41000000, v14
	v_mul_f32 v16, v16, v15
	v_mul_f32 v17, v17, v15
	v_mul_f32 v18, v18, v15
	v_mul_f32 v19, v19, v15
	v_mul_f32 v20, v20, v15
	v_mul_f32 v21, v21, v15
	v_mul_f32 v22, v22, v15
	v_mul_f32 v23, v23, v15
	v_mul_f32 v24, v24, v15
	v_mul_f32 v25, v25, v15
	v_mul_f32 v26, v26, v15
	v_mul_f32 v27, v27, v15
	v_mul_f32 v28, v28, v15
	v_mul_f32 v29, v29, v15
	v_mul_f32 v30, v30, v15
	v_mul_f32 v31, v31, v15
	v_mul_f32 v32, v32, v15
	v_mul_f32 v33, v33, v15
	v_mul_f32 v34, v34, v15
	v_mul_f32 v35, v35, v15
	v_mul_f32 v36, v36, v15
	v_mul_f32 v37, v37, v15
	v_mul_f32 v38, v38, v15
	v_mul_f32 v39, v39, v15
	v_mul_f32 v40, v40, v15
	v_mul_f32 v41, v41, v15
	v_mul_f32 v42, v42, v15
	v_mul_f32 v43, v43, v15
	v_mul_f32 v44, v44, v15
	v_mul_f32 v45, v45, v15
	v_mul_f32 v46, v46, v15
	v_mul_f32 v47, v47, v15
	v_mul_f32 v206, v206, v15
	v_cmp_neq_f32_e64 s[36:37], 0, v205
	s_branch .Lat1_pairend
; template <int TYPE>
; __device__ __forceinline__ void attn_item(const Ctx& a, int b, int h, int qt, LAS unsigned char* lds) {
;     ...
;         for (int sub = 0; sub < 2; ++sub) {
;             if (!act[sub]) continue;
.Lat1_skip:
	s_waitcnt vmcnt(0)
	ds_write_b128 v193, v[2:5]
	ds_write_b128 v193, v[10:13] offset:9216
	ds_write_b128 v200, v[6:9]
	ds_write_b128 v200, v[136:139] offset:8192
	s_cmp_eq_u32 s13, 2
	s_cselect_b32 s8, 0x19800, 0
	s_sub_u32 s8, 0x8800, s8
	s_add_u32 s13, s13, 1
	s_cmp_eq_u32 s13, 3
	s_cselect_b32 s13, 0, s13
	s_waitcnt lgkmcnt(0)
	s_add_u32 s9, s26, 2
	s_cmp_lt_u32 s9, s30
	s_cbranch_scc0 .Lat1_mid4
	global_load_dwordx4 v[2:5], v184, s[52:53]
	global_load_dwordx4 v[6:9], v184, s[52:53] offset:1024
	global_load_dwordx4 v[10:13], v185, s[52:53]
	global_load_dwordx4 v[136:139], v185, s[52:53] offset:1024
	s_add_u32 s52, s52, 0x100000
	s_addc_u32 s53, s53, 0
.Lat1_mid4:
	v_add_u32 v193, s8, v193
	v_add_u32 v200, s8, v200
	s_barrier
	s_branch .Lat1_pairend

; template <int TYPE>
; __device__ __forceinline__ void attn_item(const Ctx& a, int b, int h, int qt, LAS unsigned char* lds) {
;     ...
;         if (kp + 1 < npair) AT_STORE(bufi ^ 1);
;         __syncthreads();
.Lat1_mid5:
	v_add_u32 v193, s8, v193
	v_add_u32 v200, s8, v200
	s_barrier

; #define LAS __attribute__((address_space(3)))
; template <int TYPE>
; __device__ __forceinline__ void attn_item(const Ctx& a, int b, int h, int qt, LAS unsigned char* lds) {
;     ...
;     for (int kp = 0; kp < npair; ++kp) {
;         const int bufi = kp & 1;
;         if (kp + 1 < npair) AT_LOAD(kp + 1);
;         LAS unsigned char* Bf = lds + bufi * BUF;
;     ...
;         if (kp + 1 < npair) AT_STORE(bufi ^ 1);
;         __syncthreads();
;     }
.Lat1_g1_end:
.Lat1_pairend:
	s_cmp_eq_u32 s12, 2
	s_cselect_b32 s8, 0x19800, 0
	s_sub_u32 s8, 0x8800, s8
	v_add_u32 v190, s8, v190
	v_add_u32 v191, s8, v191
	v_add_u32 v192, s8, v192
	s_add_u32 s12, s12, 1
	s_cmp_eq_u32 s12, 3
	s_cselect_b32 s12, 0, s12
	s_add_u32 s26, s26, 1
	s_waitcnt lgkmcnt(0)
	s_cmp_lt_u32 s26, s30
	s_cbranch_scc1 .Lat1_loop
